# merge4 redesigned: full 128-B-line LDS-DMA pieces (8 rows x 128 B), BK=64 pair-slots 2x32KB, one barrier per 32 MFMAs
# speedup vs baseline: 1.1534x; 1.0378x over previous
; template <int NI> ...
;     ...
;   const int lane = tid & 63, wid = tid >> 6, wr = wid >> 1, wc = wid & 1;
;   const int lrow = tid >> 2, lch = (tid & 3) * 8;
;   const int l15 = lane & 15, lq = lane >> 4;
;   const bf16_t* pa = A + (size_t)lrow * lda + lch;
;   const bf16_t* pb = B + (size_t)lrow * ldb + lch;
;   const size_t a64 = (size_t)64 * lda, b64 = (size_t)64 * ldb;
;   u32x4 a0[2], a1[2], b0[NB], b1[NB];
;   const int nk = K >> 5;
;   const int klast = K - 32;
;   const int wofs = lrow * GROW + lch;
;   const int raofs = (wr * 64 + l15) * GROW + lq * 8;
;   const int rbofs = 128 * GROW + (wc * (16 * NI) + l15) * GROW + lq * 8;
;     ...
;   G_LOAD(a0, b0, 0);
;   G_LOAD(a1, b1, 32);
;   __syncthreads();
;   G_WRITE(a0, b0, 0);
;   __syncthreads();
; __device__ void phase_merge4(CParams& p, int l, int tm, int tn, char* smem) {
;     ...
;   for (int kb0 = 0; kb0 < 4; kb0++) {
;     int kb = kb0;
;     asm volatile("" : "+s"(kb));
;     int tid2 = tid;
;     asm volatile("" : "+v"(tid2));
;     unsigned pk[4][4][2];
;     {
;       f32x4 acc[4][4];
;       zero_acc<4>(acc);
;       gemm_mainloop<4>(p.br + (size_t)row0 * 1024 + kb * 256, 1024,
;                        p.WbT + (((size_t)l * 4 + kb) * 1024 + col0) * 256, 256, 256, sA, sB, acc, tid2);
.LBB0_878:
	s_or_b64 exec, exec, s[20:21]
	s_mov_b64 s[42:43], s[34:35]
	s_waitcnt lgkmcnt(0)
	s_barrier
	s_lshl_b64 s[6:7], s[50:51], 12
	s_load_dwordx4 s[48:51], s[42:43], 0x1d0
	s_load_dwordx4 s[52:55], s[42:43], 0x108
	s_load_dwordx2 s[20:21], s[42:43], 0x150
	s_add_u32 s24, s6, s88
	s_addc_u32 s25, s7, s89
	s_lshl_b64 s[6:7], s[88:89], 1
	s_waitcnt lgkmcnt(0)
	s_add_u32 s44, s50, s6
	s_addc_u32 s45, s51, s7
	s_mov_b64 exec, -1
	ds_read_b128 v[252:255], v145 offset:40960
	v_cndmask_b32_e64 v0, 0, 1, s[84:85]
	v_cmp_ne_u32_e64 s[40:41], 1, v0
	s_load_dwordx2 s[0:1], s[34:35], 0x150
	s_load_dwordx2 s[6:7], s[34:35], 0x1d0
	s_load_dwordx2 s[8:9], s[34:35], 0x1d8
	s_load_dwordx2 s[12:13], s[34:35], 0x108
	s_load_dwordx2 s[18:19], s[34:35], 0x110
	s_lshr_b32 s2, s24, 12
	v_readlane_b32 s4, v225, 4
	v_readfirstlane_b32 s56, v147
	v_and_b32_e32 v166, 63, v147
	s_nop 3
	s_and_b32 s20, s4, 7
	s_lshl_b32 s20, s20, 3
	s_lshr_b32 s57, s4, 6
	s_add_u32 s20, s20, s57
	s_lshr_b32 s21, s4, 3
	s_and_b32 s21, s21, 7
	s_lshl_b32 s21, s21, 7
	s_lshr_b32 s57, s56, 6
	s_lshl_b32 s56, s57, 12
	v_lshrrev_b32_e32 v167, 3, v166
	s_lshl_b32 s62, s57, 5
	v_add_u32_e32 v167, s62, v167
	v_and_b32_e32 v226, 7, v166
	v_lshrrev_b32_e32 v227, 4, v166
	v_xor_b32_e32 v248, v226, v227
	v_xor_b32_e32 v249, 0, v248
	v_lshlrev_b32_e32 v249, 4, v249
	v_add_u32_e32 v250, 0, v167
	v_lshl_add_u32 v236, v250, 11, v249
	v_xor_b32_e32 v249, 4, v248
	v_lshlrev_b32_e32 v249, 4, v249
	v_add_u32_e32 v250, 8, v167
	v_lshl_add_u32 v237, v250, 11, v249
	v_xor_b32_e32 v249, 0, v248
	v_lshlrev_b32_e32 v249, 4, v249
	v_add_u32_e32 v250, 16, v167
	v_lshl_add_u32 v238, v250, 11, v249
	v_xor_b32_e32 v249, 4, v248
	v_lshlrev_b32_e32 v249, 4, v249
	v_add_u32_e32 v250, 24, v167
	v_lshl_add_u32 v239, v250, 11, v249
	s_and_b32 s63, s57, 1
	s_lshl_b32 s63, s63, 2
	v_and_b32_e32 v248, 1, v227
	v_or_b32_e32 v248, s63, v248
	v_xor_b32_e32 v248, v226, v248
	v_xor_b32_e32 v249, 0, v248
	v_lshlrev_b32_e32 v249, 4, v249
	v_add_u32_e32 v250, 0, v167
	v_lshl_add_u32 v240, v250, 9, v249
	v_lshl_add_u32 v244, v250, 11, v249
	v_xor_b32_e32 v249, 0, v248
	v_lshlrev_b32_e32 v249, 4, v249
	v_add_u32_e32 v250, 8, v167
	v_lshl_add_u32 v241, v250, 9, v249
	v_lshl_add_u32 v245, v250, 11, v249
	v_xor_b32_e32 v249, 2, v248
	v_lshlrev_b32_e32 v249, 4, v249
	v_add_u32_e32 v250, 16, v167
	v_lshl_add_u32 v242, v250, 9, v249
	v_lshl_add_u32 v246, v250, 11, v249
	v_xor_b32_e32 v249, 2, v248
	v_lshlrev_b32_e32 v249, 4, v249
	v_add_u32_e32 v250, 24, v167
	v_lshl_add_u32 v243, v250, 9, v249
	v_lshl_add_u32 v247, v250, 11, v249
	v_and_b32_e32 v167, 15, v166
	v_lshrrev_b32_e32 v227, 4, v166
	s_lshr_b32 s62, s57, 1
	s_and_b32 s63, s57, 1
	s_lshl_b32 s92, s62, 6
	s_lshl_b32 s93, s63, 6
	v_lshrrev_b32_e32 v226, 1, v167
	v_xor_b32_e32 v226, v227, v226
	v_lshlrev_b32_e32 v226, 4, v226
	v_add_u32_e32 v248, s92, v167
	v_lshl_add_u32 v248, v248, 7, v226
	v_xor_b32_e32 v249, 64, v248
	v_lshrrev_b32_e32 v226, 2, v167
	v_lshrrev_b32_e32 v250, 1, v167
	v_and_b32_e32 v250, 1, v250
	v_lshl_or_b32 v250, v226, 1, v250
	v_xor_b32_e32 v250, v227, v250
	v_lshlrev_b32_e32 v250, 4, v250
	v_and_b32_e32 v251, 3, v167
	v_lshl_add_u32 v251, v226, 4, v251
	v_add_u32_e32 v251, s93, v251
	v_lshl_add_u32 v250, v251, 7, v250
	v_add_u32_e32 v250, 0x4000, v250
	v_xor_b32_e32 v251, 64, v250
	v_add_u32_e32 v226, s92, v167
	v_lshlrev_b32_e32 v226, 10, v226
	v_lshl_add_u32 v226, v227, 4, v226
	v_add_u32_e32 v226, s93, v226
	v_lshlrev_b32_e32 v144, 1, v226
	s_waitcnt lgkmcnt(0)
	s_mov_b32 s22, 0
	s_lshr_b32 s62, s22, 2
	s_lshl_b32 s62, s62, 6
	s_add_u32 s62, s62, s20
	s_lshl_b32 s62, s62, 18
	s_and_b32 s63, s22, 3
	s_lshl_b32 s92, s63, 9
	s_add_u32 s62, s62, s92
	s_add_u32 s24, s6, s62
	s_addc_u32 s25, s7, 0
	s_lshl_b32 s92, s2, 2
	s_add_u32 s92, s92, s63
	s_lshl_b32 s92, s92, 10
	s_add_u32 s92, s92, s21
	s_lshl_b32 s93, s92, 9
	s_add_u32 s26, s18, s93
	s_addc_u32 s27, s19, 0
	s_barrier
	s_add_u32 m0, s56, 0x0
	s_nop 0
	global_load_lds_dwordx4 v236, s[24:25]
	s_add_u32 m0, s56, 0x400
	s_nop 0
	global_load_lds_dwordx4 v237, s[24:25]
	s_add_u32 m0, s56, 0x800
	s_nop 0
	global_load_lds_dwordx4 v238, s[24:25]
	s_add_u32 m0, s56, 0xc00
	s_nop 0
	global_load_lds_dwordx4 v239, s[24:25]
	s_add_u32 m0, s56, 0x4000
	s_nop 0
	global_load_lds_dwordx4 v240, s[26:27]
	s_add_u32 m0, s56, 0x4400
	s_nop 0
	global_load_lds_dwordx4 v241, s[26:27]
	s_add_u32 m0, s56, 0x4800
	s_nop 0
	global_load_lds_dwordx4 v242, s[26:27]
	s_add_u32 m0, s56, 0x4c00
	s_nop 0
	global_load_lds_dwordx4 v243, s[26:27]
	s_add_u32 s24, s24, 128
	s_addc_u32 s25, s25, 0
	s_add_u32 s26, s26, 128
	s_addc_u32 s27, s27, 0
	s_add_u32 m0, s56, 0x8000
	s_nop 0
	global_load_lds_dwordx4 v236, s[24:25]
	s_add_u32 m0, s56, 0x8400
	s_nop 0
	global_load_lds_dwordx4 v237, s[24:25]
	s_add_u32 m0, s56, 0x8800
	s_nop 0
	global_load_lds_dwordx4 v238, s[24:25]
	s_add_u32 m0, s56, 0x8c00
	s_nop 0
	global_load_lds_dwordx4 v239, s[24:25]
	s_add_u32 m0, s56, 0xc000
	s_nop 0
	global_load_lds_dwordx4 v240, s[26:27]
	s_add_u32 m0, s56, 0xc400
	s_nop 0
	global_load_lds_dwordx4 v241, s[26:27]
	s_add_u32 m0, s56, 0xc800
	s_nop 0
	global_load_lds_dwordx4 v242, s[26:27]
	s_add_u32 m0, s56, 0xcc00
	s_nop 0
	global_load_lds_dwordx4 v243, s[26:27]
	s_add_u32 s24, s24, 128
	s_addc_u32 s25, s25, 0
	s_add_u32 s26, s26, 128
	s_addc_u32 s27, s27, 0
	s_waitcnt vmcnt(8)
	s_barrier
	ds_read_b128 v[168:171], v248 offset:0
	ds_read_b128 v[184:187], v250 offset:0
	ds_read_b128 v[172:175], v248 offset:2048
	ds_read_b128 v[188:191], v250 offset:512
	ds_read_b128 v[176:179], v248 offset:4096
	ds_read_b128 v[192:195], v250 offset:1024
	ds_read_b128 v[180:183], v248 offset:6144
	ds_read_b128 v[196:199], v250 offset:1536

; template <int NI> ...
;     ...
;   for (int kt = 0; kt < nk; kt += 2) {
;     G_LOAD(a0, b0, min((kt + 2) * 32, klast));
;     G_COMPUTE(0);
;     G_WRITE(a1, b1, 1);
;     __syncthreads();
;     G_LOAD(a1, b1, min((kt + 3) * 32, klast));
;     G_COMPUTE(1);
;     G_WRITE(a0, b0, 0);
;     __syncthreads();
;   }
; __device__ void phase_merge4(CParams& p, int l, int tm, int tn, char* smem) {
;     ...
;       gemm_mainloop<4>(p.br + (size_t)row0 * 1024 + kb * 256, 1024,
;                        p.WbT + (((size_t)l * 4 + kb) * 1024 + col0) * 256, 256, 256, sA, sB, acc, tid2);
.Lmg4_nozero:
	s_waitcnt lgkmcnt(0)
	v_mfma_f32_16x16x32_bf16 v[0:3], v[184:187], v[168:171], 0
	ds_read_b128 v[200:203], v249 offset:0
	v_mfma_f32_16x16x32_bf16 v[4:7], v[188:191], v[168:171], 0
	ds_read_b128 v[216:219], v251 offset:0
	v_mfma_f32_16x16x32_bf16 v[8:11], v[192:195], v[168:171], 0
	ds_read_b128 v[204:207], v249 offset:2048
	v_mfma_f32_16x16x32_bf16 v[12:15], v[196:199], v[168:171], 0
	ds_read_b128 v[220:223], v251 offset:512
	v_mfma_f32_16x16x32_bf16 v[16:19], v[184:187], v[172:175], 0
	ds_read_b128 v[208:211], v249 offset:4096
	v_mfma_f32_16x16x32_bf16 v[20:23], v[188:191], v[172:175], 0
	ds_read_b128 v[228:231], v251 offset:1024
	v_mfma_f32_16x16x32_bf16 v[24:27], v[192:195], v[172:175], 0
	ds_read_b128 v[212:215], v249 offset:6144
	v_mfma_f32_16x16x32_bf16 v[28:31], v[196:199], v[172:175], 0
	ds_read_b128 v[232:235], v251 offset:1536
	v_mfma_f32_16x16x32_bf16 v[32:35], v[184:187], v[176:179], 0
	v_mfma_f32_16x16x32_bf16 v[36:39], v[188:191], v[176:179], 0
	v_mfma_f32_16x16x32_bf16 v[40:43], v[192:195], v[176:179], 0
	v_mfma_f32_16x16x32_bf16 v[44:47], v[196:199], v[176:179], 0
	v_mfma_f32_16x16x32_bf16 v[48:51], v[184:187], v[180:183], 0
	v_mfma_f32_16x16x32_bf16 v[52:55], v[188:191], v[180:183], 0
	v_mfma_f32_16x16x32_bf16 v[56:59], v[192:195], v[180:183], 0
	v_mfma_f32_16x16x32_bf16 v[60:63], v[196:199], v[180:183], 0
	s_waitcnt vmcnt(0) lgkmcnt(0)
	s_barrier
	s_add_u32 m0, s56, 0x0
	s_nop 0
	global_load_lds_dwordx4 v236, s[24:25]
	s_add_u32 m0, s56, 0x400
	s_nop 0
	global_load_lds_dwordx4 v237, s[24:25]
	s_add_u32 m0, s56, 0x800
	s_nop 0
	global_load_lds_dwordx4 v238, s[24:25]
	s_add_u32 m0, s56, 0xc00
	s_nop 0
	global_load_lds_dwordx4 v239, s[24:25]
	s_add_u32 m0, s56, 0x4000
	s_nop 0
	global_load_lds_dwordx4 v240, s[26:27]
	s_add_u32 m0, s56, 0x4400
	s_nop 0
	global_load_lds_dwordx4 v241, s[26:27]
	s_add_u32 m0, s56, 0x4800
	s_nop 0
	global_load_lds_dwordx4 v242, s[26:27]
	s_add_u32 m0, s56, 0x4c00
	s_nop 0
	global_load_lds_dwordx4 v243, s[26:27]
	s_add_u32 s24, s24, 128
	s_addc_u32 s25, s25, 0
	s_add_u32 s26, s26, 128
	s_addc_u32 s27, s27, 0
	v_mfma_f32_16x16x32_bf16 v[0:3], v[216:219], v[200:203], v[0:3]
	ds_read_b128 v[168:171], v248 offset:32768
	v_mfma_f32_16x16x32_bf16 v[4:7], v[220:223], v[200:203], v[4:7]
	ds_read_b128 v[184:187], v250 offset:32768
	v_mfma_f32_16x16x32_bf16 v[8:11], v[228:231], v[200:203], v[8:11]
	ds_read_b128 v[172:175], v248 offset:34816
	v_mfma_f32_16x16x32_bf16 v[12:15], v[232:235], v[200:203], v[12:15]
	ds_read_b128 v[188:191], v250 offset:33280
	v_mfma_f32_16x16x32_bf16 v[16:19], v[216:219], v[204:207], v[16:19]
	ds_read_b128 v[176:179], v248 offset:36864
	v_mfma_f32_16x16x32_bf16 v[20:23], v[220:223], v[204:207], v[20:23]
	ds_read_b128 v[192:195], v250 offset:33792
	v_mfma_f32_16x16x32_bf16 v[24:27], v[228:231], v[204:207], v[24:27]
	ds_read_b128 v[180:183], v248 offset:38912
	v_mfma_f32_16x16x32_bf16 v[28:31], v[232:235], v[204:207], v[28:31]
	ds_read_b128 v[196:199], v250 offset:34304
	v_mfma_f32_16x16x32_bf16 v[32:35], v[216:219], v[208:211], v[32:35]
	v_mfma_f32_16x16x32_bf16 v[36:39], v[220:223], v[208:211], v[36:39]
	v_mfma_f32_16x16x32_bf16 v[40:43], v[228:231], v[208:211], v[40:43]
	v_mfma_f32_16x16x32_bf16 v[44:47], v[232:235], v[208:211], v[44:47]
	v_mfma_f32_16x16x32_bf16 v[48:51], v[216:219], v[212:215], v[48:51]
	v_mfma_f32_16x16x32_bf16 v[52:55], v[220:223], v[212:215], v[52:55]
	v_mfma_f32_16x16x32_bf16 v[56:59], v[228:231], v[212:215], v[56:59]
	v_mfma_f32_16x16x32_bf16 v[60:63], v[232:235], v[212:215], v[60:63]
	s_waitcnt lgkmcnt(0)
	v_mfma_f32_16x16x32_bf16 v[0:3], v[184:187], v[168:171], v[0:3]
	ds_read_b128 v[200:203], v249 offset:32768
	v_mfma_f32_16x16x32_bf16 v[4:7], v[188:191], v[168:171], v[4:7]
	ds_read_b128 v[216:219], v251 offset:32768
	v_mfma_f32_16x16x32_bf16 v[8:11], v[192:195], v[168:171], v[8:11]
	ds_read_b128 v[204:207], v249 offset:34816
	v_mfma_f32_16x16x32_bf16 v[12:15], v[196:199], v[168:171], v[12:15]
	ds_read_b128 v[220:223], v251 offset:33280
	v_mfma_f32_16x16x32_bf16 v[16:19], v[184:187], v[172:175], v[16:19]
	ds_read_b128 v[208:211], v249 offset:36864
	v_mfma_f32_16x16x32_bf16 v[20:23], v[188:191], v[172:175], v[20:23]
	ds_read_b128 v[228:231], v251 offset:33792
	v_mfma_f32_16x16x32_bf16 v[24:27], v[192:195], v[172:175], v[24:27]
	ds_read_b128 v[212:215], v249 offset:38912
	v_mfma_f32_16x16x32_bf16 v[28:31], v[196:199], v[172:175], v[28:31]
	ds_read_b128 v[232:235], v251 offset:34304
	v_mfma_f32_16x16x32_bf16 v[32:35], v[184:187], v[176:179], v[32:35]
	v_mfma_f32_16x16x32_bf16 v[36:39], v[188:191], v[176:179], v[36:39]
	v_mfma_f32_16x16x32_bf16 v[40:43], v[192:195], v[176:179], v[40:43]
	v_mfma_f32_16x16x32_bf16 v[44:47], v[196:199], v[176:179], v[44:47]
	v_mfma_f32_16x16x32_bf16 v[48:51], v[184:187], v[180:183], v[48:51]
	v_mfma_f32_16x16x32_bf16 v[52:55], v[188:191], v[180:183], v[52:55]
	v_mfma_f32_16x16x32_bf16 v[56:59], v[192:195], v[180:183], v[56:59]
	v_mfma_f32_16x16x32_bf16 v[60:63], v[196:199], v[180:183], v[60:63]
	s_waitcnt vmcnt(0) lgkmcnt(0)
	s_barrier
; template <int NI> ...
;     ...
;   for (int kt = 0; kt < nk; kt += 2) {
;     G_LOAD(a0, b0, min((kt + 2) * 32, klast));
;     G_COMPUTE(0);
;     G_WRITE(a1, b1, 1);
;     __syncthreads();
;     G_LOAD(a1, b1, min((kt + 3) * 32, klast));
;     G_COMPUTE(1);
;     G_WRITE(a0, b0, 0);
;     __syncthreads();
;   }
; __device__ void phase_merge4(CParams& p, int l, int tm, int tn, char* smem) {
;     ...
;     f32x4 acc[4][4];
;     zero_acc<4>(acc);
;     asm volatile("" : "+v"(tid2));
;     gemm_mainloop<4>(p.hbuf + (size_t)row0 * DM, DM,
;                      p.WgT + (((size_t)l * 4 + kb) * 1024 + col0) * 1024, 1024, 1024, sA, sB, acc, tid2);
	s_add_u32 m0, s56, 0x8000
	s_nop 0
	global_load_lds_dwordx4 v236, s[24:25]
	s_add_u32 m0, s56, 0x8400
	s_nop 0
	global_load_lds_dwordx4 v237, s[24:25]
	s_add_u32 m0, s56, 0x8800
	s_nop 0
	global_load_lds_dwordx4 v238, s[24:25]
	s_add_u32 m0, s56, 0x8c00
	s_nop 0
	global_load_lds_dwordx4 v239, s[24:25]
	s_add_u32 m0, s56, 0xc000
	s_nop 0
	global_load_lds_dwordx4 v240, s[26:27]
	s_add_u32 m0, s56, 0xc400
	s_nop 0
	global_load_lds_dwordx4 v241, s[26:27]
	s_add_u32 m0, s56, 0xc800
	s_nop 0
	global_load_lds_dwordx4 v242, s[26:27]
	s_add_u32 m0, s56, 0xcc00
	s_nop 0
	global_load_lds_dwordx4 v243, s[26:27]
	s_add_u32 s24, s24, 128
	s_addc_u32 s25, s25, 0
	s_add_u32 s26, s26, 128
	s_addc_u32 s27, s27, 0
	v_mfma_f32_16x16x32_bf16 v[0:3], v[216:219], v[200:203], v[0:3]
	ds_read_b128 v[168:171], v248 offset:0
	v_mfma_f32_16x16x32_bf16 v[4:7], v[220:223], v[200:203], v[4:7]
	ds_read_b128 v[184:187], v250 offset:0
	v_mfma_f32_16x16x32_bf16 v[8:11], v[228:231], v[200:203], v[8:11]
	ds_read_b128 v[172:175], v248 offset:2048
	v_mfma_f32_16x16x32_bf16 v[12:15], v[232:235], v[200:203], v[12:15]
	ds_read_b128 v[188:191], v250 offset:512
	v_mfma_f32_16x16x32_bf16 v[16:19], v[216:219], v[204:207], v[16:19]
	ds_read_b128 v[176:179], v248 offset:4096
	v_mfma_f32_16x16x32_bf16 v[20:23], v[220:223], v[204:207], v[20:23]
	ds_read_b128 v[192:195], v250 offset:1024
	v_mfma_f32_16x16x32_bf16 v[24:27], v[228:231], v[204:207], v[24:27]
	ds_read_b128 v[180:183], v248 offset:6144
	v_mfma_f32_16x16x32_bf16 v[28:31], v[232:235], v[204:207], v[28:31]
	ds_read_b128 v[196:199], v250 offset:1536
	v_mfma_f32_16x16x32_bf16 v[32:35], v[216:219], v[208:211], v[32:35]
	v_mfma_f32_16x16x32_bf16 v[36:39], v[220:223], v[208:211], v[36:39]
	v_mfma_f32_16x16x32_bf16 v[40:43], v[228:231], v[208:211], v[40:43]
	v_mfma_f32_16x16x32_bf16 v[44:47], v[232:235], v[208:211], v[44:47]
	v_mfma_f32_16x16x32_bf16 v[48:51], v[216:219], v[212:215], v[48:51]
	v_mfma_f32_16x16x32_bf16 v[52:55], v[220:223], v[212:215], v[52:55]
	v_mfma_f32_16x16x32_bf16 v[56:59], v[228:231], v[212:215], v[56:59]
	v_mfma_f32_16x16x32_bf16 v[60:63], v[232:235], v[212:215], v[60:63]
	s_waitcnt lgkmcnt(0)
	v_mfma_f32_16x16x32_bf16 v[0:3], v[184:187], v[168:171], v[0:3]
	ds_read_b128 v[200:203], v249 offset:0
	v_mfma_f32_16x16x32_bf16 v[4:7], v[188:191], v[168:171], v[4:7]
	ds_read_b128 v[216:219], v251 offset:0
	v_mfma_f32_16x16x32_bf16 v[8:11], v[192:195], v[168:171], v[8:11]
	ds_read_b128 v[204:207], v249 offset:2048
	v_mfma_f32_16x16x32_bf16 v[12:15], v[196:199], v[168:171], v[12:15]
	ds_read_b128 v[220:223], v251 offset:512
	v_mfma_f32_16x16x32_bf16 v[16:19], v[184:187], v[172:175], v[16:19]
	ds_read_b128 v[208:211], v249 offset:4096
	v_mfma_f32_16x16x32_bf16 v[20:23], v[188:191], v[172:175], v[20:23]
	ds_read_b128 v[228:231], v251 offset:1024
	v_mfma_f32_16x16x32_bf16 v[24:27], v[192:195], v[172:175], v[24:27]
	ds_read_b128 v[212:215], v249 offset:6144
	v_mfma_f32_16x16x32_bf16 v[28:31], v[196:199], v[172:175], v[28:31]
	ds_read_b128 v[232:235], v251 offset:1536
	v_mfma_f32_16x16x32_bf16 v[32:35], v[184:187], v[176:179], v[32:35]
	v_mfma_f32_16x16x32_bf16 v[36:39], v[188:191], v[176:179], v[36:39]
	v_mfma_f32_16x16x32_bf16 v[40:43], v[192:195], v[176:179], v[40:43]
	v_mfma_f32_16x16x32_bf16 v[44:47], v[196:199], v[176:179], v[44:47]
	v_mfma_f32_16x16x32_bf16 v[48:51], v[184:187], v[180:183], v[48:51]
	v_mfma_f32_16x16x32_bf16 v[52:55], v[188:191], v[180:183], v[52:55]
	v_mfma_f32_16x16x32_bf16 v[56:59], v[192:195], v[180:183], v[56:59]
	v_mfma_f32_16x16x32_bf16 v[60:63], v[196:199], v[180:183], v[60:63]
	s_waitcnt vmcnt(0) lgkmcnt(0)
	s_barrier
	s_mov_b64 s[24:25], s[50:51]
	s_mov_b64 s[26:27], s[54:55]
	s_add_u32 m0, s56, 0x0
	s_nop 0
	global_load_lds_dwordx4 v236, s[24:25]
	s_add_u32 m0, s56, 0x400
	s_nop 0
	global_load_lds_dwordx4 v237, s[24:25]
	s_add_u32 m0, s56, 0x800
	s_nop 0
	global_load_lds_dwordx4 v238, s[24:25]
	s_add_u32 m0, s56, 0xc00
	s_nop 0
	global_load_lds_dwordx4 v239, s[24:25]
	s_add_u32 m0, s56, 0x4000
	s_nop 0
	global_load_lds_dwordx4 v244, s[26:27]
	s_add_u32 m0, s56, 0x4400
	s_nop 0
	global_load_lds_dwordx4 v245, s[26:27]
	s_add_u32 m0, s56, 0x4800
	s_nop 0
	global_load_lds_dwordx4 v246, s[26:27]
	s_add_u32 m0, s56, 0x4c00
	s_nop 0
	global_load_lds_dwordx4 v247, s[26:27]
	s_add_u32 s24, s24, 128
	s_addc_u32 s25, s25, 0
	s_add_u32 s26, s26, 128
	s_addc_u32 s27, s27, 0
	v_mfma_f32_16x16x32_bf16 v[0:3], v[216:219], v[200:203], v[0:3]
	ds_read_b128 v[168:171], v248 offset:32768
	v_mfma_f32_16x16x32_bf16 v[4:7], v[220:223], v[200:203], v[4:7]
	ds_read_b128 v[184:187], v250 offset:32768
	v_mfma_f32_16x16x32_bf16 v[8:11], v[228:231], v[200:203], v[8:11]
	ds_read_b128 v[172:175], v248 offset:34816
	v_mfma_f32_16x16x32_bf16 v[12:15], v[232:235], v[200:203], v[12:15]
	ds_read_b128 v[188:191], v250 offset:33280
	v_mfma_f32_16x16x32_bf16 v[16:19], v[216:219], v[204:207], v[16:19]
	ds_read_b128 v[176:179], v248 offset:36864
	v_mfma_f32_16x16x32_bf16 v[20:23], v[220:223], v[204:207], v[20:23]
	ds_read_b128 v[192:195], v250 offset:33792
	v_mfma_f32_16x16x32_bf16 v[24:27], v[228:231], v[204:207], v[24:27]
	ds_read_b128 v[180:183], v248 offset:38912
	v_mfma_f32_16x16x32_bf16 v[28:31], v[232:235], v[204:207], v[28:31]
	ds_read_b128 v[196:199], v250 offset:34304
	v_mfma_f32_16x16x32_bf16 v[32:35], v[216:219], v[208:211], v[32:35]
	v_mfma_f32_16x16x32_bf16 v[36:39], v[220:223], v[208:211], v[36:39]
	v_mfma_f32_16x16x32_bf16 v[40:43], v[228:231], v[208:211], v[40:43]
	v_mfma_f32_16x16x32_bf16 v[44:47], v[232:235], v[208:211], v[44:47]
	v_mfma_f32_16x16x32_bf16 v[48:51], v[216:219], v[212:215], v[48:51]
	v_mfma_f32_16x16x32_bf16 v[52:55], v[220:223], v[212:215], v[52:55]
	v_mfma_f32_16x16x32_bf16 v[56:59], v[228:231], v[212:215], v[56:59]
	v_mfma_f32_16x16x32_bf16 v[60:63], v[232:235], v[212:215], v[60:63]
	s_waitcnt lgkmcnt(0)
; template <int NI> ...
;     ...
;   for (int kt = 0; kt < nk; kt += 2) {
;     G_LOAD(a0, b0, min((kt + 2) * 32, klast));
;     G_COMPUTE(0);
;     G_WRITE(a1, b1, 1);
;     __syncthreads();
;     G_LOAD(a1, b1, min((kt + 3) * 32, klast));
;     G_COMPUTE(1);
;     G_WRITE(a0, b0, 0);
;     __syncthreads();
;   }
; __device__ void phase_merge4(CParams& p, int l, int tm, int tn, char* smem) {
;     ...
; #pragma unroll
;       for (int mi = 0; mi < 4; mi++)
; #pragma unroll
;         for (int ni = 0; ni < 4; ni++) {
;           pk[mi][ni][0] = (unsigned)f2bf(acc[mi][ni][0]) | ((unsigned)f2bf(acc[mi][ni][1]) << 16);
;           pk[mi][ni][1] = (unsigned)f2bf(acc[mi][ni][2]) | ((unsigned)f2bf(acc[mi][ni][3]) << 16);
;         }
;     }
;     f32x4 acc[4][4];
;     zero_acc<4>(acc);
;     asm volatile("" : "+v"(tid2));
;     gemm_mainloop<4>(p.hbuf + (size_t)row0 * DM, DM,
;                      p.WgT + (((size_t)l * 4 + kb) * 1024 + col0) * 1024, 1024, 1024, sA, sB, acc, tid2);
	v_mfma_f32_16x16x32_bf16 v[0:3], v[184:187], v[168:171], v[0:3]
	ds_read_b128 v[200:203], v249 offset:32768
	v_mfma_f32_16x16x32_bf16 v[4:7], v[188:191], v[168:171], v[4:7]
	ds_read_b128 v[216:219], v251 offset:32768
	v_mfma_f32_16x16x32_bf16 v[8:11], v[192:195], v[168:171], v[8:11]
	ds_read_b128 v[204:207], v249 offset:34816
	v_mfma_f32_16x16x32_bf16 v[12:15], v[196:199], v[168:171], v[12:15]
	ds_read_b128 v[220:223], v251 offset:33280
	v_mfma_f32_16x16x32_bf16 v[16:19], v[184:187], v[172:175], v[16:19]
	ds_read_b128 v[208:211], v249 offset:36864
	v_mfma_f32_16x16x32_bf16 v[20:23], v[188:191], v[172:175], v[20:23]
	ds_read_b128 v[228:231], v251 offset:33792
	v_mfma_f32_16x16x32_bf16 v[24:27], v[192:195], v[172:175], v[24:27]
	ds_read_b128 v[212:215], v249 offset:38912
	v_mfma_f32_16x16x32_bf16 v[28:31], v[196:199], v[172:175], v[28:31]
	ds_read_b128 v[232:235], v251 offset:34304
	v_mfma_f32_16x16x32_bf16 v[32:35], v[184:187], v[176:179], v[32:35]
	v_mfma_f32_16x16x32_bf16 v[36:39], v[188:191], v[176:179], v[36:39]
	v_mfma_f32_16x16x32_bf16 v[40:43], v[192:195], v[176:179], v[40:43]
	v_mfma_f32_16x16x32_bf16 v[44:47], v[196:199], v[176:179], v[44:47]
	v_mfma_f32_16x16x32_bf16 v[48:51], v[184:187], v[180:183], v[48:51]
	v_mfma_f32_16x16x32_bf16 v[52:55], v[188:191], v[180:183], v[52:55]
	v_mfma_f32_16x16x32_bf16 v[56:59], v[192:195], v[180:183], v[56:59]
	v_mfma_f32_16x16x32_bf16 v[60:63], v[196:199], v[180:183], v[60:63]
	s_waitcnt vmcnt(0) lgkmcnt(0)
	s_barrier
	s_add_u32 m0, s56, 0x8000
	s_nop 0
	global_load_lds_dwordx4 v236, s[24:25]
	s_add_u32 m0, s56, 0x8400
	s_nop 0
	global_load_lds_dwordx4 v237, s[24:25]
	s_add_u32 m0, s56, 0x8800
	s_nop 0
	global_load_lds_dwordx4 v238, s[24:25]
	s_add_u32 m0, s56, 0x8c00
	s_nop 0
	global_load_lds_dwordx4 v239, s[24:25]
	s_add_u32 m0, s56, 0xc000
	s_nop 0
	global_load_lds_dwordx4 v244, s[26:27]
	s_add_u32 m0, s56, 0xc400
	s_nop 0
	global_load_lds_dwordx4 v245, s[26:27]
	s_add_u32 m0, s56, 0xc800
	s_nop 0
	global_load_lds_dwordx4 v246, s[26:27]
	s_add_u32 m0, s56, 0xcc00
	s_nop 0
	global_load_lds_dwordx4 v247, s[26:27]
	s_add_u32 s24, s24, 128
	s_addc_u32 s25, s25, 0
	s_add_u32 s26, s26, 128
	s_addc_u32 s27, s27, 0
	v_mfma_f32_16x16x32_bf16 v[0:3], v[216:219], v[200:203], v[0:3]
	ds_read_b128 v[168:171], v248 offset:0
	v_mfma_f32_16x16x32_bf16 v[4:7], v[220:223], v[200:203], v[4:7]
	ds_read_b128 v[184:187], v250 offset:0
	v_mfma_f32_16x16x32_bf16 v[8:11], v[228:231], v[200:203], v[8:11]
	ds_read_b128 v[172:175], v248 offset:2048
	v_mfma_f32_16x16x32_bf16 v[12:15], v[232:235], v[200:203], v[12:15]
	ds_read_b128 v[188:191], v250 offset:512
	v_mfma_f32_16x16x32_bf16 v[16:19], v[216:219], v[204:207], v[16:19]
	ds_read_b128 v[176:179], v248 offset:4096
	v_mfma_f32_16x16x32_bf16 v[20:23], v[220:223], v[204:207], v[20:23]
	ds_read_b128 v[192:195], v250 offset:1024
	v_mfma_f32_16x16x32_bf16 v[24:27], v[228:231], v[204:207], v[24:27]
	ds_read_b128 v[180:183], v248 offset:6144
	v_mfma_f32_16x16x32_bf16 v[28:31], v[232:235], v[204:207], v[28:31]
	ds_read_b128 v[196:199], v250 offset:1536
	v_mfma_f32_16x16x32_bf16 v[32:35], v[216:219], v[208:211], v[32:35]
	v_mfma_f32_16x16x32_bf16 v[36:39], v[220:223], v[208:211], v[36:39]
	v_mfma_f32_16x16x32_bf16 v[40:43], v[228:231], v[208:211], v[40:43]
	v_mfma_f32_16x16x32_bf16 v[44:47], v[232:235], v[208:211], v[44:47]
	v_mfma_f32_16x16x32_bf16 v[48:51], v[216:219], v[212:215], v[48:51]
	v_mfma_f32_16x16x32_bf16 v[52:55], v[220:223], v[212:215], v[52:55]
	v_mfma_f32_16x16x32_bf16 v[56:59], v[228:231], v[212:215], v[56:59]
	v_mfma_f32_16x16x32_bf16 v[60:63], v[232:235], v[212:215], v[60:63]
	s_nop 15
	s_nop 7
	v_cvt_pk_bf16_f32 v128, v0, v1
	v_cvt_pk_bf16_f32 v129, v2, v3
	v_cvt_pk_bf16_f32 v130, v4, v5
	v_cvt_pk_bf16_f32 v131, v6, v7
	v_cvt_pk_bf16_f32 v132, v8, v9
	v_cvt_pk_bf16_f32 v133, v10, v11
	v_cvt_pk_bf16_f32 v134, v12, v13
	v_cvt_pk_bf16_f32 v135, v14, v15
	v_cvt_pk_bf16_f32 v136, v16, v17
	v_cvt_pk_bf16_f32 v137, v18, v19
	v_cvt_pk_bf16_f32 v138, v20, v21
	v_cvt_pk_bf16_f32 v139, v22, v23
	v_cvt_pk_bf16_f32 v140, v24, v25
	v_cvt_pk_bf16_f32 v141, v26, v27
	v_cvt_pk_bf16_f32 v142, v28, v29
	v_cvt_pk_bf16_f32 v143, v30, v31
	v_cvt_pk_bf16_f32 v148, v32, v33
	v_cvt_pk_bf16_f32 v149, v34, v35
	v_cvt_pk_bf16_f32 v150, v36, v37
	v_cvt_pk_bf16_f32 v151, v38, v39
	v_cvt_pk_bf16_f32 v152, v40, v41
	v_cvt_pk_bf16_f32 v153, v42, v43
	v_cvt_pk_bf16_f32 v154, v44, v45
	v_cvt_pk_bf16_f32 v155, v46, v47
	v_cvt_pk_bf16_f32 v156, v48, v49
	v_cvt_pk_bf16_f32 v157, v50, v51
	v_cvt_pk_bf16_f32 v158, v52, v53
	v_cvt_pk_bf16_f32 v159, v54, v55
	v_cvt_pk_bf16_f32 v160, v56, v57
	v_cvt_pk_bf16_f32 v161, v58, v59
	v_cvt_pk_bf16_f32 v162, v60, v61
	v_cvt_pk_bf16_f32 v163, v62, v63
	s_waitcnt lgkmcnt(0)
	v_mfma_f32_16x16x32_bf16 v[0:3], v[184:187], v[168:171], 0
	ds_read_b128 v[200:203], v249 offset:0
	v_mfma_f32_16x16x32_bf16 v[4:7], v[188:191], v[168:171], 0
	ds_read_b128 v[216:219], v251 offset:0
	v_mfma_f32_16x16x32_bf16 v[8:11], v[192:195], v[168:171], 0
	ds_read_b128 v[204:207], v249 offset:2048
	v_mfma_f32_16x16x32_bf16 v[12:15], v[196:199], v[168:171], 0
	ds_read_b128 v[220:223], v251 offset:512
	v_mfma_f32_16x16x32_bf16 v[16:19], v[184:187], v[172:175], 0
	ds_read_b128 v[208:211], v249 offset:4096
	v_mfma_f32_16x16x32_bf16 v[20:23], v[188:191], v[172:175], 0
	ds_read_b128 v[228:231], v251 offset:1024
	v_mfma_f32_16x16x32_bf16 v[24:27], v[192:195], v[172:175], 0
	ds_read_b128 v[212:215], v249 offset:6144
	v_mfma_f32_16x16x32_bf16 v[28:31], v[196:199], v[172:175], 0
	ds_read_b128 v[232:235], v251 offset:1536
	v_mfma_f32_16x16x32_bf16 v[32:35], v[184:187], v[176:179], 0
	v_mfma_f32_16x16x32_bf16 v[36:39], v[188:191], v[176:179], 0
	v_mfma_f32_16x16x32_bf16 v[40:43], v[192:195], v[176:179], 0
	v_mfma_f32_16x16x32_bf16 v[44:47], v[196:199], v[176:179], 0
	v_mfma_f32_16x16x32_bf16 v[48:51], v[184:187], v[180:183], 0
	v_mfma_f32_16x16x32_bf16 v[52:55], v[188:191], v[180:183], 0
	v_mfma_f32_16x16x32_bf16 v[56:59], v[192:195], v[180:183], 0
	v_mfma_f32_16x16x32_bf16 v[60:63], v[196:199], v[180:183], 0
	s_waitcnt vmcnt(0) lgkmcnt(0)
	s_barrier
; template <int NI> ...
;     ...
;   for (int kt = 0; kt < nk; kt += 2) {
;     G_LOAD(a0, b0, min((kt + 2) * 32, klast));
;     G_COMPUTE(0);
;     G_WRITE(a1, b1, 1);
;     __syncthreads();
;     G_LOAD(a1, b1, min((kt + 3) * 32, klast));
;     G_COMPUTE(1);
;     G_WRITE(a0, b0, 0);
;     __syncthreads();
;   }
; __device__ void phase_merge4(CParams& p, int l, int tm, int tn, char* smem) {
;     ...
;     gemm_mainloop<4>(p.hbuf + (size_t)row0 * DM, DM,
;                      p.WgT + (((size_t)l * 4 + kb) * 1024 + col0) * 1024, 1024, 1024, sA, sB, acc, tid2);
	s_add_u32 m0, s56, 0x0
	s_nop 0
	global_load_lds_dwordx4 v236, s[24:25]
	s_add_u32 m0, s56, 0x400
	s_nop 0
	global_load_lds_dwordx4 v237, s[24:25]
	s_add_u32 m0, s56, 0x800
	s_nop 0
	global_load_lds_dwordx4 v238, s[24:25]
	s_add_u32 m0, s56, 0xc00
	s_nop 0
	global_load_lds_dwordx4 v239, s[24:25]
	s_add_u32 m0, s56, 0x4000
	s_nop 0
	global_load_lds_dwordx4 v244, s[26:27]
	s_add_u32 m0, s56, 0x4400
	s_nop 0
	global_load_lds_dwordx4 v245, s[26:27]
	s_add_u32 m0, s56, 0x4800
	s_nop 0
	global_load_lds_dwordx4 v246, s[26:27]
	s_add_u32 m0, s56, 0x4c00
	s_nop 0
	global_load_lds_dwordx4 v247, s[26:27]
	s_add_u32 s24, s24, 128
	s_addc_u32 s25, s25, 0
	s_add_u32 s26, s26, 128
	s_addc_u32 s27, s27, 0
	v_mfma_f32_16x16x32_bf16 v[0:3], v[216:219], v[200:203], v[0:3]
	ds_read_b128 v[168:171], v248 offset:32768
	v_mfma_f32_16x16x32_bf16 v[4:7], v[220:223], v[200:203], v[4:7]
	ds_read_b128 v[184:187], v250 offset:32768
	v_mfma_f32_16x16x32_bf16 v[8:11], v[228:231], v[200:203], v[8:11]
	ds_read_b128 v[172:175], v248 offset:34816
	v_mfma_f32_16x16x32_bf16 v[12:15], v[232:235], v[200:203], v[12:15]
	ds_read_b128 v[188:191], v250 offset:33280
	v_mfma_f32_16x16x32_bf16 v[16:19], v[216:219], v[204:207], v[16:19]
	ds_read_b128 v[176:179], v248 offset:36864
	v_mfma_f32_16x16x32_bf16 v[20:23], v[220:223], v[204:207], v[20:23]
	ds_read_b128 v[192:195], v250 offset:33792
	v_mfma_f32_16x16x32_bf16 v[24:27], v[228:231], v[204:207], v[24:27]
	ds_read_b128 v[180:183], v248 offset:38912
	v_mfma_f32_16x16x32_bf16 v[28:31], v[232:235], v[204:207], v[28:31]
	ds_read_b128 v[196:199], v250 offset:34304
	v_mfma_f32_16x16x32_bf16 v[32:35], v[216:219], v[208:211], v[32:35]
	v_mfma_f32_16x16x32_bf16 v[36:39], v[220:223], v[208:211], v[36:39]
	v_mfma_f32_16x16x32_bf16 v[40:43], v[228:231], v[208:211], v[40:43]
	v_mfma_f32_16x16x32_bf16 v[44:47], v[232:235], v[208:211], v[44:47]
	v_mfma_f32_16x16x32_bf16 v[48:51], v[216:219], v[212:215], v[48:51]
	v_mfma_f32_16x16x32_bf16 v[52:55], v[220:223], v[212:215], v[52:55]
	v_mfma_f32_16x16x32_bf16 v[56:59], v[228:231], v[212:215], v[56:59]
	v_mfma_f32_16x16x32_bf16 v[60:63], v[232:235], v[212:215], v[60:63]
	s_waitcnt lgkmcnt(0)
	v_mfma_f32_16x16x32_bf16 v[0:3], v[184:187], v[168:171], v[0:3]
	ds_read_b128 v[200:203], v249 offset:32768
	v_mfma_f32_16x16x32_bf16 v[4:7], v[188:191], v[168:171], v[4:7]
	ds_read_b128 v[216:219], v251 offset:32768
	v_mfma_f32_16x16x32_bf16 v[8:11], v[192:195], v[168:171], v[8:11]
	ds_read_b128 v[204:207], v249 offset:34816
	v_mfma_f32_16x16x32_bf16 v[12:15], v[196:199], v[168:171], v[12:15]
	ds_read_b128 v[220:223], v251 offset:33280
	v_mfma_f32_16x16x32_bf16 v[16:19], v[184:187], v[172:175], v[16:19]
	ds_read_b128 v[208:211], v249 offset:36864
	v_mfma_f32_16x16x32_bf16 v[20:23], v[188:191], v[172:175], v[20:23]
	ds_read_b128 v[228:231], v251 offset:33792
	v_mfma_f32_16x16x32_bf16 v[24:27], v[192:195], v[172:175], v[24:27]
	ds_read_b128 v[212:215], v249 offset:38912
	v_mfma_f32_16x16x32_bf16 v[28:31], v[196:199], v[172:175], v[28:31]
	ds_read_b128 v[232:235], v251 offset:34304
	v_mfma_f32_16x16x32_bf16 v[32:35], v[184:187], v[176:179], v[32:35]
	v_mfma_f32_16x16x32_bf16 v[36:39], v[188:191], v[176:179], v[36:39]
	v_mfma_f32_16x16x32_bf16 v[40:43], v[192:195], v[176:179], v[40:43]
	v_mfma_f32_16x16x32_bf16 v[44:47], v[196:199], v[176:179], v[44:47]
	v_mfma_f32_16x16x32_bf16 v[48:51], v[184:187], v[180:183], v[48:51]
	v_mfma_f32_16x16x32_bf16 v[52:55], v[188:191], v[180:183], v[52:55]
	v_mfma_f32_16x16x32_bf16 v[56:59], v[192:195], v[180:183], v[56:59]
	v_mfma_f32_16x16x32_bf16 v[60:63], v[196:199], v[180:183], v[60:63]
	s_waitcnt vmcnt(0) lgkmcnt(0)
	s_barrier
	s_add_u32 m0, s56, 0x8000
	s_nop 0
	global_load_lds_dwordx4 v236, s[24:25]
	s_add_u32 m0, s56, 0x8400
	s_nop 0
	global_load_lds_dwordx4 v237, s[24:25]
	s_add_u32 m0, s56, 0x8800
	s_nop 0
	global_load_lds_dwordx4 v238, s[24:25]
	s_add_u32 m0, s56, 0x8c00
	s_nop 0
	global_load_lds_dwordx4 v239, s[24:25]
	s_add_u32 m0, s56, 0xc000
	s_nop 0
	global_load_lds_dwordx4 v244, s[26:27]
	s_add_u32 m0, s56, 0xc400
	s_nop 0
	global_load_lds_dwordx4 v245, s[26:27]
	s_add_u32 m0, s56, 0xc800
	s_nop 0
	global_load_lds_dwordx4 v246, s[26:27]
	s_add_u32 m0, s56, 0xcc00
	s_nop 0
	global_load_lds_dwordx4 v247, s[26:27]
	s_add_u32 s24, s24, 128
	s_addc_u32 s25, s25, 0
	s_add_u32 s26, s26, 128
	s_addc_u32 s27, s27, 0
	v_mfma_f32_16x16x32_bf16 v[0:3], v[216:219], v[200:203], v[0:3]
	ds_read_b128 v[168:171], v248 offset:0
	v_mfma_f32_16x16x32_bf16 v[4:7], v[220:223], v[200:203], v[4:7]
	ds_read_b128 v[184:187], v250 offset:0
	v_mfma_f32_16x16x32_bf16 v[8:11], v[228:231], v[200:203], v[8:11]
	ds_read_b128 v[172:175], v248 offset:2048
	v_mfma_f32_16x16x32_bf16 v[12:15], v[232:235], v[200:203], v[12:15]
	ds_read_b128 v[188:191], v250 offset:512
	v_mfma_f32_16x16x32_bf16 v[16:19], v[216:219], v[204:207], v[16:19]
	ds_read_b128 v[176:179], v248 offset:4096
	v_mfma_f32_16x16x32_bf16 v[20:23], v[220:223], v[204:207], v[20:23]
	ds_read_b128 v[192:195], v250 offset:1024
	v_mfma_f32_16x16x32_bf16 v[24:27], v[228:231], v[204:207], v[24:27]
	ds_read_b128 v[180:183], v248 offset:6144
	v_mfma_f32_16x16x32_bf16 v[28:31], v[232:235], v[204:207], v[28:31]
	ds_read_b128 v[196:199], v250 offset:1536
	v_mfma_f32_16x16x32_bf16 v[32:35], v[216:219], v[208:211], v[32:35]
	v_mfma_f32_16x16x32_bf16 v[36:39], v[220:223], v[208:211], v[36:39]
	v_mfma_f32_16x16x32_bf16 v[40:43], v[228:231], v[208:211], v[40:43]
	v_mfma_f32_16x16x32_bf16 v[44:47], v[232:235], v[208:211], v[44:47]
	v_mfma_f32_16x16x32_bf16 v[48:51], v[216:219], v[212:215], v[48:51]
	v_mfma_f32_16x16x32_bf16 v[52:55], v[220:223], v[212:215], v[52:55]
	v_mfma_f32_16x16x32_bf16 v[56:59], v[228:231], v[212:215], v[56:59]
	v_mfma_f32_16x16x32_bf16 v[60:63], v[232:235], v[212:215], v[60:63]
	s_waitcnt lgkmcnt(0)
; template <int NI> ...
;     ...
;   for (int kt = 0; kt < nk; kt += 2) {
;     G_LOAD(a0, b0, min((kt + 2) * 32, klast));
;     G_COMPUTE(0);
;     G_WRITE(a1, b1, 1);
;     __syncthreads();
;     G_LOAD(a1, b1, min((kt + 3) * 32, klast));
;     G_COMPUTE(1);
;     G_WRITE(a0, b0, 0);
;     __syncthreads();
;   }
; __device__ void phase_merge4(CParams& p, int l, int tm, int tn, char* smem) {
;     ...
;     gemm_mainloop<4>(p.hbuf + (size_t)row0 * DM, DM,
;                      p.WgT + (((size_t)l * 4 + kb) * 1024 + col0) * 1024, 1024, 1024, sA, sB, acc, tid2);
	v_mfma_f32_16x16x32_bf16 v[0:3], v[184:187], v[168:171], v[0:3]
	ds_read_b128 v[200:203], v249 offset:0
	v_mfma_f32_16x16x32_bf16 v[4:7], v[188:191], v[168:171], v[4:7]
	ds_read_b128 v[216:219], v251 offset:0
	v_mfma_f32_16x16x32_bf16 v[8:11], v[192:195], v[168:171], v[8:11]
	ds_read_b128 v[204:207], v249 offset:2048
	v_mfma_f32_16x16x32_bf16 v[12:15], v[196:199], v[168:171], v[12:15]
	ds_read_b128 v[220:223], v251 offset:512
	v_mfma_f32_16x16x32_bf16 v[16:19], v[184:187], v[172:175], v[16:19]
	ds_read_b128 v[208:211], v249 offset:4096
	v_mfma_f32_16x16x32_bf16 v[20:23], v[188:191], v[172:175], v[20:23]
	ds_read_b128 v[228:231], v251 offset:1024
	v_mfma_f32_16x16x32_bf16 v[24:27], v[192:195], v[172:175], v[24:27]
	ds_read_b128 v[212:215], v249 offset:6144
	v_mfma_f32_16x16x32_bf16 v[28:31], v[196:199], v[172:175], v[28:31]
	ds_read_b128 v[232:235], v251 offset:1536
	v_mfma_f32_16x16x32_bf16 v[32:35], v[184:187], v[176:179], v[32:35]
	v_mfma_f32_16x16x32_bf16 v[36:39], v[188:191], v[176:179], v[36:39]
	v_mfma_f32_16x16x32_bf16 v[40:43], v[192:195], v[176:179], v[40:43]
	v_mfma_f32_16x16x32_bf16 v[44:47], v[196:199], v[176:179], v[44:47]
	v_mfma_f32_16x16x32_bf16 v[48:51], v[184:187], v[180:183], v[48:51]
	v_mfma_f32_16x16x32_bf16 v[52:55], v[188:191], v[180:183], v[52:55]
	v_mfma_f32_16x16x32_bf16 v[56:59], v[192:195], v[180:183], v[56:59]
	v_mfma_f32_16x16x32_bf16 v[60:63], v[196:199], v[180:183], v[60:63]
	s_waitcnt vmcnt(0) lgkmcnt(0)
	s_barrier
	s_add_u32 m0, s56, 0x0
	s_nop 0
	global_load_lds_dwordx4 v236, s[24:25]
	s_add_u32 m0, s56, 0x400
	s_nop 0
	global_load_lds_dwordx4 v237, s[24:25]
	s_add_u32 m0, s56, 0x800
	s_nop 0
	global_load_lds_dwordx4 v238, s[24:25]
	s_add_u32 m0, s56, 0xc00
	s_nop 0
	global_load_lds_dwordx4 v239, s[24:25]
	s_add_u32 m0, s56, 0x4000
	s_nop 0
	global_load_lds_dwordx4 v244, s[26:27]
	s_add_u32 m0, s56, 0x4400
	s_nop 0
	global_load_lds_dwordx4 v245, s[26:27]
	s_add_u32 m0, s56, 0x4800
	s_nop 0
	global_load_lds_dwordx4 v246, s[26:27]
	s_add_u32 m0, s56, 0x4c00
	s_nop 0
	global_load_lds_dwordx4 v247, s[26:27]
	s_add_u32 s24, s24, 128
	s_addc_u32 s25, s25, 0
	s_add_u32 s26, s26, 128
	s_addc_u32 s27, s27, 0
	v_mfma_f32_16x16x32_bf16 v[0:3], v[216:219], v[200:203], v[0:3]
	ds_read_b128 v[168:171], v248 offset:32768
	v_mfma_f32_16x16x32_bf16 v[4:7], v[220:223], v[200:203], v[4:7]
	ds_read_b128 v[184:187], v250 offset:32768
	v_mfma_f32_16x16x32_bf16 v[8:11], v[228:231], v[200:203], v[8:11]
	ds_read_b128 v[172:175], v248 offset:34816
	v_mfma_f32_16x16x32_bf16 v[12:15], v[232:235], v[200:203], v[12:15]
	ds_read_b128 v[188:191], v250 offset:33280
	v_mfma_f32_16x16x32_bf16 v[16:19], v[216:219], v[204:207], v[16:19]
	ds_read_b128 v[176:179], v248 offset:36864
	v_mfma_f32_16x16x32_bf16 v[20:23], v[220:223], v[204:207], v[20:23]
	ds_read_b128 v[192:195], v250 offset:33792
	v_mfma_f32_16x16x32_bf16 v[24:27], v[228:231], v[204:207], v[24:27]
	ds_read_b128 v[180:183], v248 offset:38912
	v_mfma_f32_16x16x32_bf16 v[28:31], v[232:235], v[204:207], v[28:31]
	ds_read_b128 v[196:199], v250 offset:34304
	v_mfma_f32_16x16x32_bf16 v[32:35], v[216:219], v[208:211], v[32:35]
	v_mfma_f32_16x16x32_bf16 v[36:39], v[220:223], v[208:211], v[36:39]
	v_mfma_f32_16x16x32_bf16 v[40:43], v[228:231], v[208:211], v[40:43]
	v_mfma_f32_16x16x32_bf16 v[44:47], v[232:235], v[208:211], v[44:47]
	v_mfma_f32_16x16x32_bf16 v[48:51], v[216:219], v[212:215], v[48:51]
	v_mfma_f32_16x16x32_bf16 v[52:55], v[220:223], v[212:215], v[52:55]
	v_mfma_f32_16x16x32_bf16 v[56:59], v[228:231], v[212:215], v[56:59]
	v_mfma_f32_16x16x32_bf16 v[60:63], v[232:235], v[212:215], v[60:63]
	s_waitcnt lgkmcnt(0)
	v_mfma_f32_16x16x32_bf16 v[0:3], v[184:187], v[168:171], v[0:3]
	ds_read_b128 v[200:203], v249 offset:32768
	v_mfma_f32_16x16x32_bf16 v[4:7], v[188:191], v[168:171], v[4:7]
	ds_read_b128 v[216:219], v251 offset:32768
	v_mfma_f32_16x16x32_bf16 v[8:11], v[192:195], v[168:171], v[8:11]
	ds_read_b128 v[204:207], v249 offset:34816
	v_mfma_f32_16x16x32_bf16 v[12:15], v[196:199], v[168:171], v[12:15]
	ds_read_b128 v[220:223], v251 offset:33280
	v_mfma_f32_16x16x32_bf16 v[16:19], v[184:187], v[172:175], v[16:19]
	ds_read_b128 v[208:211], v249 offset:36864
	v_mfma_f32_16x16x32_bf16 v[20:23], v[188:191], v[172:175], v[20:23]
	ds_read_b128 v[228:231], v251 offset:33792
	v_mfma_f32_16x16x32_bf16 v[24:27], v[192:195], v[172:175], v[24:27]
	ds_read_b128 v[212:215], v249 offset:38912
	v_mfma_f32_16x16x32_bf16 v[28:31], v[196:199], v[172:175], v[28:31]
	ds_read_b128 v[232:235], v251 offset:34304
	v_mfma_f32_16x16x32_bf16 v[32:35], v[184:187], v[176:179], v[32:35]
	v_mfma_f32_16x16x32_bf16 v[36:39], v[188:191], v[176:179], v[36:39]
	v_mfma_f32_16x16x32_bf16 v[40:43], v[192:195], v[176:179], v[40:43]
	v_mfma_f32_16x16x32_bf16 v[44:47], v[196:199], v[176:179], v[44:47]
	v_mfma_f32_16x16x32_bf16 v[48:51], v[184:187], v[180:183], v[48:51]
	v_mfma_f32_16x16x32_bf16 v[52:55], v[188:191], v[180:183], v[52:55]
	v_mfma_f32_16x16x32_bf16 v[56:59], v[192:195], v[180:183], v[56:59]
	v_mfma_f32_16x16x32_bf16 v[60:63], v[196:199], v[180:183], v[60:63]
	s_waitcnt vmcnt(0) lgkmcnt(0)
	s_barrier
; template <int NI> ...
;     ...
;   for (int kt = 0; kt < nk; kt += 2) {
;     G_LOAD(a0, b0, min((kt + 2) * 32, klast));
;     G_COMPUTE(0);
;     G_WRITE(a1, b1, 1);
;     __syncthreads();
;     G_LOAD(a1, b1, min((kt + 3) * 32, klast));
;     G_COMPUTE(1);
;     G_WRITE(a0, b0, 0);
;     __syncthreads();
;   }
; __device__ void phase_merge4(CParams& p, int l, int tm, int tn, char* smem) {
;     ...
;     gemm_mainloop<4>(p.hbuf + (size_t)row0 * DM, DM,
;                      p.WgT + (((size_t)l * 4 + kb) * 1024 + col0) * 1024, 1024, 1024, sA, sB, acc, tid2);
	s_add_u32 m0, s56, 0x8000
	s_nop 0
	global_load_lds_dwordx4 v236, s[24:25]
	s_add_u32 m0, s56, 0x8400
	s_nop 0
	global_load_lds_dwordx4 v237, s[24:25]
	s_add_u32 m0, s56, 0x8800
	s_nop 0
	global_load_lds_dwordx4 v238, s[24:25]
	s_add_u32 m0, s56, 0x8c00
	s_nop 0
	global_load_lds_dwordx4 v239, s[24:25]
	s_add_u32 m0, s56, 0xc000
	s_nop 0
	global_load_lds_dwordx4 v244, s[26:27]
	s_add_u32 m0, s56, 0xc400
	s_nop 0
	global_load_lds_dwordx4 v245, s[26:27]
	s_add_u32 m0, s56, 0xc800
	s_nop 0
	global_load_lds_dwordx4 v246, s[26:27]
	s_add_u32 m0, s56, 0xcc00
	s_nop 0
	global_load_lds_dwordx4 v247, s[26:27]
	s_add_u32 s24, s24, 128
	s_addc_u32 s25, s25, 0
	s_add_u32 s26, s26, 128
	s_addc_u32 s27, s27, 0
	v_mfma_f32_16x16x32_bf16 v[0:3], v[216:219], v[200:203], v[0:3]
	ds_read_b128 v[168:171], v248 offset:0
	v_mfma_f32_16x16x32_bf16 v[4:7], v[220:223], v[200:203], v[4:7]
	ds_read_b128 v[184:187], v250 offset:0
	v_mfma_f32_16x16x32_bf16 v[8:11], v[228:231], v[200:203], v[8:11]
	ds_read_b128 v[172:175], v248 offset:2048
	v_mfma_f32_16x16x32_bf16 v[12:15], v[232:235], v[200:203], v[12:15]
	ds_read_b128 v[188:191], v250 offset:512
	v_mfma_f32_16x16x32_bf16 v[16:19], v[216:219], v[204:207], v[16:19]
	ds_read_b128 v[176:179], v248 offset:4096
	v_mfma_f32_16x16x32_bf16 v[20:23], v[220:223], v[204:207], v[20:23]
	ds_read_b128 v[192:195], v250 offset:1024
	v_mfma_f32_16x16x32_bf16 v[24:27], v[228:231], v[204:207], v[24:27]
	ds_read_b128 v[180:183], v248 offset:6144
	v_mfma_f32_16x16x32_bf16 v[28:31], v[232:235], v[204:207], v[28:31]
	ds_read_b128 v[196:199], v250 offset:1536
	v_mfma_f32_16x16x32_bf16 v[32:35], v[216:219], v[208:211], v[32:35]
	v_mfma_f32_16x16x32_bf16 v[36:39], v[220:223], v[208:211], v[36:39]
	v_mfma_f32_16x16x32_bf16 v[40:43], v[228:231], v[208:211], v[40:43]
	v_mfma_f32_16x16x32_bf16 v[44:47], v[232:235], v[208:211], v[44:47]
	v_mfma_f32_16x16x32_bf16 v[48:51], v[216:219], v[212:215], v[48:51]
	v_mfma_f32_16x16x32_bf16 v[52:55], v[220:223], v[212:215], v[52:55]
	v_mfma_f32_16x16x32_bf16 v[56:59], v[228:231], v[212:215], v[56:59]
	v_mfma_f32_16x16x32_bf16 v[60:63], v[232:235], v[212:215], v[60:63]
	s_waitcnt lgkmcnt(0)
	v_mfma_f32_16x16x32_bf16 v[0:3], v[184:187], v[168:171], v[0:3]
	ds_read_b128 v[200:203], v249 offset:0
	v_mfma_f32_16x16x32_bf16 v[4:7], v[188:191], v[168:171], v[4:7]
	ds_read_b128 v[216:219], v251 offset:0
	v_mfma_f32_16x16x32_bf16 v[8:11], v[192:195], v[168:171], v[8:11]
	ds_read_b128 v[204:207], v249 offset:2048
	v_mfma_f32_16x16x32_bf16 v[12:15], v[196:199], v[168:171], v[12:15]
	ds_read_b128 v[220:223], v251 offset:512
	v_mfma_f32_16x16x32_bf16 v[16:19], v[184:187], v[172:175], v[16:19]
	ds_read_b128 v[208:211], v249 offset:4096
	v_mfma_f32_16x16x32_bf16 v[20:23], v[188:191], v[172:175], v[20:23]
	ds_read_b128 v[228:231], v251 offset:1024
	v_mfma_f32_16x16x32_bf16 v[24:27], v[192:195], v[172:175], v[24:27]
	ds_read_b128 v[212:215], v249 offset:6144
	v_mfma_f32_16x16x32_bf16 v[28:31], v[196:199], v[172:175], v[28:31]
	ds_read_b128 v[232:235], v251 offset:1536
	v_mfma_f32_16x16x32_bf16 v[32:35], v[184:187], v[176:179], v[32:35]
	v_mfma_f32_16x16x32_bf16 v[36:39], v[188:191], v[176:179], v[36:39]
	v_mfma_f32_16x16x32_bf16 v[40:43], v[192:195], v[176:179], v[40:43]
	v_mfma_f32_16x16x32_bf16 v[44:47], v[196:199], v[176:179], v[44:47]
	v_mfma_f32_16x16x32_bf16 v[48:51], v[184:187], v[180:183], v[48:51]
	v_mfma_f32_16x16x32_bf16 v[52:55], v[188:191], v[180:183], v[52:55]
	v_mfma_f32_16x16x32_bf16 v[56:59], v[192:195], v[180:183], v[56:59]
	v_mfma_f32_16x16x32_bf16 v[60:63], v[196:199], v[180:183], v[60:63]
	s_waitcnt vmcnt(0) lgkmcnt(0)
	s_barrier
	s_add_u32 m0, s56, 0x0
	s_nop 0
	global_load_lds_dwordx4 v236, s[24:25]
	s_add_u32 m0, s56, 0x400
	s_nop 0
	global_load_lds_dwordx4 v237, s[24:25]
	s_add_u32 m0, s56, 0x800
	s_nop 0
	global_load_lds_dwordx4 v238, s[24:25]
	s_add_u32 m0, s56, 0xc00
	s_nop 0
	global_load_lds_dwordx4 v239, s[24:25]
	s_add_u32 m0, s56, 0x4000
	s_nop 0
	global_load_lds_dwordx4 v244, s[26:27]
	s_add_u32 m0, s56, 0x4400
	s_nop 0
	global_load_lds_dwordx4 v245, s[26:27]
	s_add_u32 m0, s56, 0x4800
	s_nop 0
	global_load_lds_dwordx4 v246, s[26:27]
	s_add_u32 m0, s56, 0x4c00
	s_nop 0
	global_load_lds_dwordx4 v247, s[26:27]
	s_add_u32 s24, s24, 128
	s_addc_u32 s25, s25, 0
	s_add_u32 s26, s26, 128
	s_addc_u32 s27, s27, 0
	v_mfma_f32_16x16x32_bf16 v[0:3], v[216:219], v[200:203], v[0:3]
	ds_read_b128 v[168:171], v248 offset:32768
	v_mfma_f32_16x16x32_bf16 v[4:7], v[220:223], v[200:203], v[4:7]
	ds_read_b128 v[184:187], v250 offset:32768
	v_mfma_f32_16x16x32_bf16 v[8:11], v[228:231], v[200:203], v[8:11]
	ds_read_b128 v[172:175], v248 offset:34816
	v_mfma_f32_16x16x32_bf16 v[12:15], v[232:235], v[200:203], v[12:15]
	ds_read_b128 v[188:191], v250 offset:33280
	v_mfma_f32_16x16x32_bf16 v[16:19], v[216:219], v[204:207], v[16:19]
	ds_read_b128 v[176:179], v248 offset:36864
	v_mfma_f32_16x16x32_bf16 v[20:23], v[220:223], v[204:207], v[20:23]
	ds_read_b128 v[192:195], v250 offset:33792
	v_mfma_f32_16x16x32_bf16 v[24:27], v[228:231], v[204:207], v[24:27]
	ds_read_b128 v[180:183], v248 offset:38912
	v_mfma_f32_16x16x32_bf16 v[28:31], v[232:235], v[204:207], v[28:31]
	ds_read_b128 v[196:199], v250 offset:34304
	v_mfma_f32_16x16x32_bf16 v[32:35], v[216:219], v[208:211], v[32:35]
	v_mfma_f32_16x16x32_bf16 v[36:39], v[220:223], v[208:211], v[36:39]
	v_mfma_f32_16x16x32_bf16 v[40:43], v[228:231], v[208:211], v[40:43]
	v_mfma_f32_16x16x32_bf16 v[44:47], v[232:235], v[208:211], v[44:47]
	v_mfma_f32_16x16x32_bf16 v[48:51], v[216:219], v[212:215], v[48:51]
	v_mfma_f32_16x16x32_bf16 v[52:55], v[220:223], v[212:215], v[52:55]
	v_mfma_f32_16x16x32_bf16 v[56:59], v[228:231], v[212:215], v[56:59]
	v_mfma_f32_16x16x32_bf16 v[60:63], v[232:235], v[212:215], v[60:63]
	s_waitcnt lgkmcnt(0)
; template <int NI> ...
;     ...
;   for (int kt = 0; kt < nk; kt += 2) {
;     G_LOAD(a0, b0, min((kt + 2) * 32, klast));
;     G_COMPUTE(0);
;     G_WRITE(a1, b1, 1);
;     __syncthreads();
;     G_LOAD(a1, b1, min((kt + 3) * 32, klast));
;     G_COMPUTE(1);
;     G_WRITE(a0, b0, 0);
;     __syncthreads();
;   }
; __device__ void phase_merge4(CParams& p, int l, int tm, int tn, char* smem) {
;     ...
;     gemm_mainloop<4>(p.hbuf + (size_t)row0 * DM, DM,
;                      p.WgT + (((size_t)l * 4 + kb) * 1024 + col0) * 1024, 1024, 1024, sA, sB, acc, tid2);
	v_mfma_f32_16x16x32_bf16 v[0:3], v[184:187], v[168:171], v[0:3]
	ds_read_b128 v[200:203], v249 offset:32768
	v_mfma_f32_16x16x32_bf16 v[4:7], v[188:191], v[168:171], v[4:7]
	ds_read_b128 v[216:219], v251 offset:32768
	v_mfma_f32_16x16x32_bf16 v[8:11], v[192:195], v[168:171], v[8:11]
	ds_read_b128 v[204:207], v249 offset:34816
	v_mfma_f32_16x16x32_bf16 v[12:15], v[196:199], v[168:171], v[12:15]
	ds_read_b128 v[220:223], v251 offset:33280
	v_mfma_f32_16x16x32_bf16 v[16:19], v[184:187], v[172:175], v[16:19]
	ds_read_b128 v[208:211], v249 offset:36864
	v_mfma_f32_16x16x32_bf16 v[20:23], v[188:191], v[172:175], v[20:23]
	ds_read_b128 v[228:231], v251 offset:33792
	v_mfma_f32_16x16x32_bf16 v[24:27], v[192:195], v[172:175], v[24:27]
	ds_read_b128 v[212:215], v249 offset:38912
	v_mfma_f32_16x16x32_bf16 v[28:31], v[196:199], v[172:175], v[28:31]
	ds_read_b128 v[232:235], v251 offset:34304
	v_mfma_f32_16x16x32_bf16 v[32:35], v[184:187], v[176:179], v[32:35]
	v_mfma_f32_16x16x32_bf16 v[36:39], v[188:191], v[176:179], v[36:39]
	v_mfma_f32_16x16x32_bf16 v[40:43], v[192:195], v[176:179], v[40:43]
	v_mfma_f32_16x16x32_bf16 v[44:47], v[196:199], v[176:179], v[44:47]
	v_mfma_f32_16x16x32_bf16 v[48:51], v[184:187], v[180:183], v[48:51]
	v_mfma_f32_16x16x32_bf16 v[52:55], v[188:191], v[180:183], v[52:55]
	v_mfma_f32_16x16x32_bf16 v[56:59], v[192:195], v[180:183], v[56:59]
	v_mfma_f32_16x16x32_bf16 v[60:63], v[196:199], v[180:183], v[60:63]
	s_waitcnt vmcnt(0) lgkmcnt(0)
	s_barrier
	s_add_u32 m0, s56, 0x8000
	s_nop 0
	global_load_lds_dwordx4 v236, s[24:25]
	s_add_u32 m0, s56, 0x8400
	s_nop 0
	global_load_lds_dwordx4 v237, s[24:25]
	s_add_u32 m0, s56, 0x8800
	s_nop 0
	global_load_lds_dwordx4 v238, s[24:25]
	s_add_u32 m0, s56, 0x8c00
	s_nop 0
	global_load_lds_dwordx4 v239, s[24:25]
	s_add_u32 m0, s56, 0xc000
	s_nop 0
	global_load_lds_dwordx4 v244, s[26:27]
	s_add_u32 m0, s56, 0xc400
	s_nop 0
	global_load_lds_dwordx4 v245, s[26:27]
	s_add_u32 m0, s56, 0xc800
	s_nop 0
	global_load_lds_dwordx4 v246, s[26:27]
	s_add_u32 m0, s56, 0xcc00
	s_nop 0
	global_load_lds_dwordx4 v247, s[26:27]
	s_add_u32 s24, s24, 128
	s_addc_u32 s25, s25, 0
	s_add_u32 s26, s26, 128
	s_addc_u32 s27, s27, 0
	v_mfma_f32_16x16x32_bf16 v[0:3], v[216:219], v[200:203], v[0:3]
	ds_read_b128 v[168:171], v248 offset:0
	v_mfma_f32_16x16x32_bf16 v[4:7], v[220:223], v[200:203], v[4:7]
	ds_read_b128 v[184:187], v250 offset:0
	v_mfma_f32_16x16x32_bf16 v[8:11], v[228:231], v[200:203], v[8:11]
	ds_read_b128 v[172:175], v248 offset:2048
	v_mfma_f32_16x16x32_bf16 v[12:15], v[232:235], v[200:203], v[12:15]
	ds_read_b128 v[188:191], v250 offset:512
	v_mfma_f32_16x16x32_bf16 v[16:19], v[216:219], v[204:207], v[16:19]
	ds_read_b128 v[176:179], v248 offset:4096
	v_mfma_f32_16x16x32_bf16 v[20:23], v[220:223], v[204:207], v[20:23]
	ds_read_b128 v[192:195], v250 offset:1024
	v_mfma_f32_16x16x32_bf16 v[24:27], v[228:231], v[204:207], v[24:27]
	ds_read_b128 v[180:183], v248 offset:6144
	v_mfma_f32_16x16x32_bf16 v[28:31], v[232:235], v[204:207], v[28:31]
	ds_read_b128 v[196:199], v250 offset:1536
	v_mfma_f32_16x16x32_bf16 v[32:35], v[216:219], v[208:211], v[32:35]
	v_mfma_f32_16x16x32_bf16 v[36:39], v[220:223], v[208:211], v[36:39]
	v_mfma_f32_16x16x32_bf16 v[40:43], v[228:231], v[208:211], v[40:43]
	v_mfma_f32_16x16x32_bf16 v[44:47], v[232:235], v[208:211], v[44:47]
	v_mfma_f32_16x16x32_bf16 v[48:51], v[216:219], v[212:215], v[48:51]
	v_mfma_f32_16x16x32_bf16 v[52:55], v[220:223], v[212:215], v[52:55]
	v_mfma_f32_16x16x32_bf16 v[56:59], v[228:231], v[212:215], v[56:59]
	v_mfma_f32_16x16x32_bf16 v[60:63], v[232:235], v[212:215], v[60:63]
	s_waitcnt lgkmcnt(0)
	v_mfma_f32_16x16x32_bf16 v[0:3], v[184:187], v[168:171], v[0:3]
	ds_read_b128 v[200:203], v249 offset:0
	v_mfma_f32_16x16x32_bf16 v[4:7], v[188:191], v[168:171], v[4:7]
	ds_read_b128 v[216:219], v251 offset:0
	v_mfma_f32_16x16x32_bf16 v[8:11], v[192:195], v[168:171], v[8:11]
	ds_read_b128 v[204:207], v249 offset:2048
	v_mfma_f32_16x16x32_bf16 v[12:15], v[196:199], v[168:171], v[12:15]
	ds_read_b128 v[220:223], v251 offset:512
	v_mfma_f32_16x16x32_bf16 v[16:19], v[184:187], v[172:175], v[16:19]
	ds_read_b128 v[208:211], v249 offset:4096
	v_mfma_f32_16x16x32_bf16 v[20:23], v[188:191], v[172:175], v[20:23]
	ds_read_b128 v[228:231], v251 offset:1024
	v_mfma_f32_16x16x32_bf16 v[24:27], v[192:195], v[172:175], v[24:27]
	ds_read_b128 v[212:215], v249 offset:6144
	v_mfma_f32_16x16x32_bf16 v[28:31], v[196:199], v[172:175], v[28:31]
	ds_read_b128 v[232:235], v251 offset:1536
	v_mfma_f32_16x16x32_bf16 v[32:35], v[184:187], v[176:179], v[32:35]
	v_mfma_f32_16x16x32_bf16 v[36:39], v[188:191], v[176:179], v[36:39]
	v_mfma_f32_16x16x32_bf16 v[40:43], v[192:195], v[176:179], v[40:43]
	v_mfma_f32_16x16x32_bf16 v[44:47], v[196:199], v[176:179], v[44:47]
	v_mfma_f32_16x16x32_bf16 v[48:51], v[184:187], v[180:183], v[48:51]
	v_mfma_f32_16x16x32_bf16 v[52:55], v[188:191], v[180:183], v[52:55]
	v_mfma_f32_16x16x32_bf16 v[56:59], v[192:195], v[180:183], v[56:59]
	v_mfma_f32_16x16x32_bf16 v[60:63], v[196:199], v[180:183], v[60:63]
	s_waitcnt vmcnt(0) lgkmcnt(0)
	s_barrier
; template <int NI> ...
;     ...
;   for (int kt = 0; kt < nk; kt += 2) {
;     G_LOAD(a0, b0, min((kt + 2) * 32, klast));
;     G_COMPUTE(0);
;     G_WRITE(a1, b1, 1);
;     __syncthreads();
;     G_LOAD(a1, b1, min((kt + 3) * 32, klast));
;     G_COMPUTE(1);
;     G_WRITE(a0, b0, 0);
;     __syncthreads();
;   }
; __device__ void phase_merge4(CParams& p, int l, int tm, int tn, char* smem) {
;     ...
;     gemm_mainloop<4>(p.hbuf + (size_t)row0 * DM, DM,
;                      p.WgT + (((size_t)l * 4 + kb) * 1024 + col0) * 1024, 1024, 1024, sA, sB, acc, tid2);
	s_add_u32 m0, s56, 0x0
	s_nop 0
	global_load_lds_dwordx4 v236, s[24:25]
	s_add_u32 m0, s56, 0x400
	s_nop 0
	global_load_lds_dwordx4 v237, s[24:25]
	s_add_u32 m0, s56, 0x800
	s_nop 0
	global_load_lds_dwordx4 v238, s[24:25]
	s_add_u32 m0, s56, 0xc00
	s_nop 0
	global_load_lds_dwordx4 v239, s[24:25]
	s_add_u32 m0, s56, 0x4000
	s_nop 0
	global_load_lds_dwordx4 v244, s[26:27]
	s_add_u32 m0, s56, 0x4400
	s_nop 0
	global_load_lds_dwordx4 v245, s[26:27]
	s_add_u32 m0, s56, 0x4800
	s_nop 0
	global_load_lds_dwordx4 v246, s[26:27]
	s_add_u32 m0, s56, 0x4c00
	s_nop 0
	global_load_lds_dwordx4 v247, s[26:27]
	s_add_u32 s24, s24, 128
	s_addc_u32 s25, s25, 0
	s_add_u32 s26, s26, 128
	s_addc_u32 s27, s27, 0
	v_mfma_f32_16x16x32_bf16 v[0:3], v[216:219], v[200:203], v[0:3]
	ds_read_b128 v[168:171], v248 offset:32768
	v_mfma_f32_16x16x32_bf16 v[4:7], v[220:223], v[200:203], v[4:7]
	ds_read_b128 v[184:187], v250 offset:32768
	v_mfma_f32_16x16x32_bf16 v[8:11], v[228:231], v[200:203], v[8:11]
	ds_read_b128 v[172:175], v248 offset:34816
	v_mfma_f32_16x16x32_bf16 v[12:15], v[232:235], v[200:203], v[12:15]
	ds_read_b128 v[188:191], v250 offset:33280
	v_mfma_f32_16x16x32_bf16 v[16:19], v[216:219], v[204:207], v[16:19]
	ds_read_b128 v[176:179], v248 offset:36864
	v_mfma_f32_16x16x32_bf16 v[20:23], v[220:223], v[204:207], v[20:23]
	ds_read_b128 v[192:195], v250 offset:33792
	v_mfma_f32_16x16x32_bf16 v[24:27], v[228:231], v[204:207], v[24:27]
	ds_read_b128 v[180:183], v248 offset:38912
	v_mfma_f32_16x16x32_bf16 v[28:31], v[232:235], v[204:207], v[28:31]
	ds_read_b128 v[196:199], v250 offset:34304
	v_mfma_f32_16x16x32_bf16 v[32:35], v[216:219], v[208:211], v[32:35]
	v_mfma_f32_16x16x32_bf16 v[36:39], v[220:223], v[208:211], v[36:39]
	v_mfma_f32_16x16x32_bf16 v[40:43], v[228:231], v[208:211], v[40:43]
	v_mfma_f32_16x16x32_bf16 v[44:47], v[232:235], v[208:211], v[44:47]
	v_mfma_f32_16x16x32_bf16 v[48:51], v[216:219], v[212:215], v[48:51]
	v_mfma_f32_16x16x32_bf16 v[52:55], v[220:223], v[212:215], v[52:55]
	v_mfma_f32_16x16x32_bf16 v[56:59], v[228:231], v[212:215], v[56:59]
	v_mfma_f32_16x16x32_bf16 v[60:63], v[232:235], v[212:215], v[60:63]
	s_waitcnt lgkmcnt(0)
	v_mfma_f32_16x16x32_bf16 v[0:3], v[184:187], v[168:171], v[0:3]
	ds_read_b128 v[200:203], v249 offset:32768
	v_mfma_f32_16x16x32_bf16 v[4:7], v[188:191], v[168:171], v[4:7]
	ds_read_b128 v[216:219], v251 offset:32768
	v_mfma_f32_16x16x32_bf16 v[8:11], v[192:195], v[168:171], v[8:11]
	ds_read_b128 v[204:207], v249 offset:34816
	v_mfma_f32_16x16x32_bf16 v[12:15], v[196:199], v[168:171], v[12:15]
	ds_read_b128 v[220:223], v251 offset:33280
	v_mfma_f32_16x16x32_bf16 v[16:19], v[184:187], v[172:175], v[16:19]
	ds_read_b128 v[208:211], v249 offset:36864
	v_mfma_f32_16x16x32_bf16 v[20:23], v[188:191], v[172:175], v[20:23]
	ds_read_b128 v[228:231], v251 offset:33792
	v_mfma_f32_16x16x32_bf16 v[24:27], v[192:195], v[172:175], v[24:27]
	ds_read_b128 v[212:215], v249 offset:38912
	v_mfma_f32_16x16x32_bf16 v[28:31], v[196:199], v[172:175], v[28:31]
	ds_read_b128 v[232:235], v251 offset:34304
	v_mfma_f32_16x16x32_bf16 v[32:35], v[184:187], v[176:179], v[32:35]
	v_mfma_f32_16x16x32_bf16 v[36:39], v[188:191], v[176:179], v[36:39]
	v_mfma_f32_16x16x32_bf16 v[40:43], v[192:195], v[176:179], v[40:43]
	v_mfma_f32_16x16x32_bf16 v[44:47], v[196:199], v[176:179], v[44:47]
	v_mfma_f32_16x16x32_bf16 v[48:51], v[184:187], v[180:183], v[48:51]
	v_mfma_f32_16x16x32_bf16 v[52:55], v[188:191], v[180:183], v[52:55]
	v_mfma_f32_16x16x32_bf16 v[56:59], v[192:195], v[180:183], v[56:59]
	v_mfma_f32_16x16x32_bf16 v[60:63], v[196:199], v[180:183], v[60:63]
	s_waitcnt vmcnt(0) lgkmcnt(0)
	s_barrier
	s_add_u32 m0, s56, 0x8000
	s_nop 0
	global_load_lds_dwordx4 v236, s[24:25]
	s_add_u32 m0, s56, 0x8400
	s_nop 0
	global_load_lds_dwordx4 v237, s[24:25]
	s_add_u32 m0, s56, 0x8800
	s_nop 0
	global_load_lds_dwordx4 v238, s[24:25]
	s_add_u32 m0, s56, 0x8c00
	s_nop 0
	global_load_lds_dwordx4 v239, s[24:25]
	s_add_u32 m0, s56, 0xc000
	s_nop 0
	global_load_lds_dwordx4 v244, s[26:27]
	s_add_u32 m0, s56, 0xc400
	s_nop 0
	global_load_lds_dwordx4 v245, s[26:27]
	s_add_u32 m0, s56, 0xc800
	s_nop 0
	global_load_lds_dwordx4 v246, s[26:27]
	s_add_u32 m0, s56, 0xcc00
	s_nop 0
	global_load_lds_dwordx4 v247, s[26:27]
	s_add_u32 s24, s24, 128
	s_addc_u32 s25, s25, 0
	s_add_u32 s26, s26, 128
	s_addc_u32 s27, s27, 0
	v_mfma_f32_16x16x32_bf16 v[0:3], v[216:219], v[200:203], v[0:3]
	ds_read_b128 v[168:171], v248 offset:0
	v_mfma_f32_16x16x32_bf16 v[4:7], v[220:223], v[200:203], v[4:7]
	ds_read_b128 v[184:187], v250 offset:0
	v_mfma_f32_16x16x32_bf16 v[8:11], v[228:231], v[200:203], v[8:11]
	ds_read_b128 v[172:175], v248 offset:2048
	v_mfma_f32_16x16x32_bf16 v[12:15], v[232:235], v[200:203], v[12:15]
	ds_read_b128 v[188:191], v250 offset:512
	v_mfma_f32_16x16x32_bf16 v[16:19], v[216:219], v[204:207], v[16:19]
	ds_read_b128 v[176:179], v248 offset:4096
	v_mfma_f32_16x16x32_bf16 v[20:23], v[220:223], v[204:207], v[20:23]
	ds_read_b128 v[192:195], v250 offset:1024
	v_mfma_f32_16x16x32_bf16 v[24:27], v[228:231], v[204:207], v[24:27]
	ds_read_b128 v[180:183], v248 offset:6144
	v_mfma_f32_16x16x32_bf16 v[28:31], v[232:235], v[204:207], v[28:31]
	ds_read_b128 v[196:199], v250 offset:1536
	v_mfma_f32_16x16x32_bf16 v[32:35], v[216:219], v[208:211], v[32:35]
	v_mfma_f32_16x16x32_bf16 v[36:39], v[220:223], v[208:211], v[36:39]
	v_mfma_f32_16x16x32_bf16 v[40:43], v[228:231], v[208:211], v[40:43]
	v_mfma_f32_16x16x32_bf16 v[44:47], v[232:235], v[208:211], v[44:47]
	v_mfma_f32_16x16x32_bf16 v[48:51], v[216:219], v[212:215], v[48:51]
	v_mfma_f32_16x16x32_bf16 v[52:55], v[220:223], v[212:215], v[52:55]
	v_mfma_f32_16x16x32_bf16 v[56:59], v[228:231], v[212:215], v[56:59]
	v_mfma_f32_16x16x32_bf16 v[60:63], v[232:235], v[212:215], v[60:63]
	s_waitcnt lgkmcnt(0)
; template <int NI> ...
;     ...
;   for (int kt = 0; kt < nk; kt += 2) {
;     G_LOAD(a0, b0, min((kt + 2) * 32, klast));
;     G_COMPUTE(0);
;     G_WRITE(a1, b1, 1);
;     __syncthreads();
;     G_LOAD(a1, b1, min((kt + 3) * 32, klast));
;     G_COMPUTE(1);
;     G_WRITE(a0, b0, 0);
;     __syncthreads();
;   }
; __device__ void phase_merge4(CParams& p, int l, int tm, int tn, char* smem) {
;     ...
;     gemm_mainloop<4>(p.hbuf + (size_t)row0 * DM, DM,
;                      p.WgT + (((size_t)l * 4 + kb) * 1024 + col0) * 1024, 1024, 1024, sA, sB, acc, tid2);
	v_mfma_f32_16x16x32_bf16 v[0:3], v[184:187], v[168:171], v[0:3]
	ds_read_b128 v[200:203], v249 offset:0
	v_mfma_f32_16x16x32_bf16 v[4:7], v[188:191], v[168:171], v[4:7]
	ds_read_b128 v[216:219], v251 offset:0
	v_mfma_f32_16x16x32_bf16 v[8:11], v[192:195], v[168:171], v[8:11]
	ds_read_b128 v[204:207], v249 offset:2048
	v_mfma_f32_16x16x32_bf16 v[12:15], v[196:199], v[168:171], v[12:15]
	ds_read_b128 v[220:223], v251 offset:512
	v_mfma_f32_16x16x32_bf16 v[16:19], v[184:187], v[172:175], v[16:19]
	ds_read_b128 v[208:211], v249 offset:4096
	v_mfma_f32_16x16x32_bf16 v[20:23], v[188:191], v[172:175], v[20:23]
	ds_read_b128 v[228:231], v251 offset:1024
	v_mfma_f32_16x16x32_bf16 v[24:27], v[192:195], v[172:175], v[24:27]
	ds_read_b128 v[212:215], v249 offset:6144
	v_mfma_f32_16x16x32_bf16 v[28:31], v[196:199], v[172:175], v[28:31]
	ds_read_b128 v[232:235], v251 offset:1536
	v_mfma_f32_16x16x32_bf16 v[32:35], v[184:187], v[176:179], v[32:35]
	v_mfma_f32_16x16x32_bf16 v[36:39], v[188:191], v[176:179], v[36:39]
	v_mfma_f32_16x16x32_bf16 v[40:43], v[192:195], v[176:179], v[40:43]
	v_mfma_f32_16x16x32_bf16 v[44:47], v[196:199], v[176:179], v[44:47]
	v_mfma_f32_16x16x32_bf16 v[48:51], v[184:187], v[180:183], v[48:51]
	v_mfma_f32_16x16x32_bf16 v[52:55], v[188:191], v[180:183], v[52:55]
	v_mfma_f32_16x16x32_bf16 v[56:59], v[192:195], v[180:183], v[56:59]
	v_mfma_f32_16x16x32_bf16 v[60:63], v[196:199], v[180:183], v[60:63]
	s_waitcnt vmcnt(0) lgkmcnt(0)
	s_barrier
	s_add_u32 m0, s56, 0x0
	s_nop 0
	global_load_lds_dwordx4 v236, s[24:25]
	s_add_u32 m0, s56, 0x400
	s_nop 0
	global_load_lds_dwordx4 v237, s[24:25]
	s_add_u32 m0, s56, 0x800
	s_nop 0
	global_load_lds_dwordx4 v238, s[24:25]
	s_add_u32 m0, s56, 0xc00
	s_nop 0
	global_load_lds_dwordx4 v239, s[24:25]
	s_add_u32 m0, s56, 0x4000
	s_nop 0
	global_load_lds_dwordx4 v244, s[26:27]
	s_add_u32 m0, s56, 0x4400
	s_nop 0
	global_load_lds_dwordx4 v245, s[26:27]
	s_add_u32 m0, s56, 0x4800
	s_nop 0
	global_load_lds_dwordx4 v246, s[26:27]
	s_add_u32 m0, s56, 0x4c00
	s_nop 0
	global_load_lds_dwordx4 v247, s[26:27]
	s_add_u32 s24, s24, 128
	s_addc_u32 s25, s25, 0
	s_add_u32 s26, s26, 128
	s_addc_u32 s27, s27, 0
	v_mfma_f32_16x16x32_bf16 v[0:3], v[216:219], v[200:203], v[0:3]
	ds_read_b128 v[168:171], v248 offset:32768
	v_mfma_f32_16x16x32_bf16 v[4:7], v[220:223], v[200:203], v[4:7]
	ds_read_b128 v[184:187], v250 offset:32768
	v_mfma_f32_16x16x32_bf16 v[8:11], v[228:231], v[200:203], v[8:11]
	ds_read_b128 v[172:175], v248 offset:34816
	v_mfma_f32_16x16x32_bf16 v[12:15], v[232:235], v[200:203], v[12:15]
	ds_read_b128 v[188:191], v250 offset:33280
	v_mfma_f32_16x16x32_bf16 v[16:19], v[216:219], v[204:207], v[16:19]
	ds_read_b128 v[176:179], v248 offset:36864
	v_mfma_f32_16x16x32_bf16 v[20:23], v[220:223], v[204:207], v[20:23]
	ds_read_b128 v[192:195], v250 offset:33792
	v_mfma_f32_16x16x32_bf16 v[24:27], v[228:231], v[204:207], v[24:27]
	ds_read_b128 v[180:183], v248 offset:38912
	v_mfma_f32_16x16x32_bf16 v[28:31], v[232:235], v[204:207], v[28:31]
	ds_read_b128 v[196:199], v250 offset:34304
	v_mfma_f32_16x16x32_bf16 v[32:35], v[216:219], v[208:211], v[32:35]
	v_mfma_f32_16x16x32_bf16 v[36:39], v[220:223], v[208:211], v[36:39]
	v_mfma_f32_16x16x32_bf16 v[40:43], v[228:231], v[208:211], v[40:43]
	v_mfma_f32_16x16x32_bf16 v[44:47], v[232:235], v[208:211], v[44:47]
	v_mfma_f32_16x16x32_bf16 v[48:51], v[216:219], v[212:215], v[48:51]
	v_mfma_f32_16x16x32_bf16 v[52:55], v[220:223], v[212:215], v[52:55]
	v_mfma_f32_16x16x32_bf16 v[56:59], v[228:231], v[212:215], v[56:59]
	v_mfma_f32_16x16x32_bf16 v[60:63], v[232:235], v[212:215], v[60:63]
	s_waitcnt lgkmcnt(0)
	v_mfma_f32_16x16x32_bf16 v[0:3], v[184:187], v[168:171], v[0:3]
	ds_read_b128 v[200:203], v249 offset:32768
	v_mfma_f32_16x16x32_bf16 v[4:7], v[188:191], v[168:171], v[4:7]
	ds_read_b128 v[216:219], v251 offset:32768
	v_mfma_f32_16x16x32_bf16 v[8:11], v[192:195], v[168:171], v[8:11]
	ds_read_b128 v[204:207], v249 offset:34816
	v_mfma_f32_16x16x32_bf16 v[12:15], v[196:199], v[168:171], v[12:15]
	ds_read_b128 v[220:223], v251 offset:33280
	v_mfma_f32_16x16x32_bf16 v[16:19], v[184:187], v[172:175], v[16:19]
	ds_read_b128 v[208:211], v249 offset:36864
	v_mfma_f32_16x16x32_bf16 v[20:23], v[188:191], v[172:175], v[20:23]
	ds_read_b128 v[228:231], v251 offset:33792
	v_mfma_f32_16x16x32_bf16 v[24:27], v[192:195], v[172:175], v[24:27]
	ds_read_b128 v[212:215], v249 offset:38912
	v_mfma_f32_16x16x32_bf16 v[28:31], v[196:199], v[172:175], v[28:31]
	ds_read_b128 v[232:235], v251 offset:34304
	v_mfma_f32_16x16x32_bf16 v[32:35], v[184:187], v[176:179], v[32:35]
	v_mfma_f32_16x16x32_bf16 v[36:39], v[188:191], v[176:179], v[36:39]
	v_mfma_f32_16x16x32_bf16 v[40:43], v[192:195], v[176:179], v[40:43]
	v_mfma_f32_16x16x32_bf16 v[44:47], v[196:199], v[176:179], v[44:47]
	v_mfma_f32_16x16x32_bf16 v[48:51], v[184:187], v[180:183], v[48:51]
	v_mfma_f32_16x16x32_bf16 v[52:55], v[188:191], v[180:183], v[52:55]
	v_mfma_f32_16x16x32_bf16 v[56:59], v[192:195], v[180:183], v[56:59]
	v_mfma_f32_16x16x32_bf16 v[60:63], v[196:199], v[180:183], v[60:63]
	s_waitcnt vmcnt(0) lgkmcnt(0)
	s_barrier
; template <int NI> ...
;     ...
;   for (int kt = 0; kt < nk; kt += 2) {
;     G_LOAD(a0, b0, min((kt + 2) * 32, klast));
;     G_COMPUTE(0);
;     G_WRITE(a1, b1, 1);
;     __syncthreads();
;     G_LOAD(a1, b1, min((kt + 3) * 32, klast));
;     G_COMPUTE(1);
;     G_WRITE(a0, b0, 0);
;     __syncthreads();
;   }
; __device__ void phase_merge4(CParams& p, int l, int tm, int tn, char* smem) {
;     ...
;     gemm_mainloop<4>(p.hbuf + (size_t)row0 * DM, DM,
;                      p.WgT + (((size_t)l * 4 + kb) * 1024 + col0) * 1024, 1024, 1024, sA, sB, acc, tid2);
	s_add_u32 m0, s56, 0x8000
	s_nop 0
	global_load_lds_dwordx4 v236, s[24:25]
	s_add_u32 m0, s56, 0x8400
	s_nop 0
	global_load_lds_dwordx4 v237, s[24:25]
	s_add_u32 m0, s56, 0x8800
	s_nop 0
	global_load_lds_dwordx4 v238, s[24:25]
	s_add_u32 m0, s56, 0x8c00
	s_nop 0
	global_load_lds_dwordx4 v239, s[24:25]
	s_add_u32 m0, s56, 0xc000
	s_nop 0
	global_load_lds_dwordx4 v244, s[26:27]
	s_add_u32 m0, s56, 0xc400
	s_nop 0
	global_load_lds_dwordx4 v245, s[26:27]
	s_add_u32 m0, s56, 0xc800
	s_nop 0
	global_load_lds_dwordx4 v246, s[26:27]
	s_add_u32 m0, s56, 0xcc00
	s_nop 0
	global_load_lds_dwordx4 v247, s[26:27]
	s_add_u32 s24, s24, 128
	s_addc_u32 s25, s25, 0
	s_add_u32 s26, s26, 128
	s_addc_u32 s27, s27, 0
	v_mfma_f32_16x16x32_bf16 v[0:3], v[216:219], v[200:203], v[0:3]
	ds_read_b128 v[168:171], v248 offset:0
	v_mfma_f32_16x16x32_bf16 v[4:7], v[220:223], v[200:203], v[4:7]
	ds_read_b128 v[184:187], v250 offset:0
	v_mfma_f32_16x16x32_bf16 v[8:11], v[228:231], v[200:203], v[8:11]
	ds_read_b128 v[172:175], v248 offset:2048
	v_mfma_f32_16x16x32_bf16 v[12:15], v[232:235], v[200:203], v[12:15]
	ds_read_b128 v[188:191], v250 offset:512
	v_mfma_f32_16x16x32_bf16 v[16:19], v[216:219], v[204:207], v[16:19]
	ds_read_b128 v[176:179], v248 offset:4096
	v_mfma_f32_16x16x32_bf16 v[20:23], v[220:223], v[204:207], v[20:23]
	ds_read_b128 v[192:195], v250 offset:1024
	v_mfma_f32_16x16x32_bf16 v[24:27], v[228:231], v[204:207], v[24:27]
	ds_read_b128 v[180:183], v248 offset:6144
	v_mfma_f32_16x16x32_bf16 v[28:31], v[232:235], v[204:207], v[28:31]
	ds_read_b128 v[196:199], v250 offset:1536
	v_mfma_f32_16x16x32_bf16 v[32:35], v[216:219], v[208:211], v[32:35]
	v_mfma_f32_16x16x32_bf16 v[36:39], v[220:223], v[208:211], v[36:39]
	v_mfma_f32_16x16x32_bf16 v[40:43], v[228:231], v[208:211], v[40:43]
	v_mfma_f32_16x16x32_bf16 v[44:47], v[232:235], v[208:211], v[44:47]
	v_mfma_f32_16x16x32_bf16 v[48:51], v[216:219], v[212:215], v[48:51]
	v_mfma_f32_16x16x32_bf16 v[52:55], v[220:223], v[212:215], v[52:55]
	v_mfma_f32_16x16x32_bf16 v[56:59], v[228:231], v[212:215], v[56:59]
	v_mfma_f32_16x16x32_bf16 v[60:63], v[232:235], v[212:215], v[60:63]
	s_waitcnt lgkmcnt(0)
	v_mfma_f32_16x16x32_bf16 v[0:3], v[184:187], v[168:171], v[0:3]
	ds_read_b128 v[200:203], v249 offset:0
	v_mfma_f32_16x16x32_bf16 v[4:7], v[188:191], v[168:171], v[4:7]
	ds_read_b128 v[216:219], v251 offset:0
	v_mfma_f32_16x16x32_bf16 v[8:11], v[192:195], v[168:171], v[8:11]
	ds_read_b128 v[204:207], v249 offset:2048
	v_mfma_f32_16x16x32_bf16 v[12:15], v[196:199], v[168:171], v[12:15]
	ds_read_b128 v[220:223], v251 offset:512
	v_mfma_f32_16x16x32_bf16 v[16:19], v[184:187], v[172:175], v[16:19]
	ds_read_b128 v[208:211], v249 offset:4096
	v_mfma_f32_16x16x32_bf16 v[20:23], v[188:191], v[172:175], v[20:23]
	ds_read_b128 v[228:231], v251 offset:1024
	v_mfma_f32_16x16x32_bf16 v[24:27], v[192:195], v[172:175], v[24:27]
	ds_read_b128 v[212:215], v249 offset:6144
	v_mfma_f32_16x16x32_bf16 v[28:31], v[196:199], v[172:175], v[28:31]
	ds_read_b128 v[232:235], v251 offset:1536
	v_mfma_f32_16x16x32_bf16 v[32:35], v[184:187], v[176:179], v[32:35]
	v_mfma_f32_16x16x32_bf16 v[36:39], v[188:191], v[176:179], v[36:39]
	v_mfma_f32_16x16x32_bf16 v[40:43], v[192:195], v[176:179], v[40:43]
	v_mfma_f32_16x16x32_bf16 v[44:47], v[196:199], v[176:179], v[44:47]
	v_mfma_f32_16x16x32_bf16 v[48:51], v[184:187], v[180:183], v[48:51]
	v_mfma_f32_16x16x32_bf16 v[52:55], v[188:191], v[180:183], v[52:55]
	v_mfma_f32_16x16x32_bf16 v[56:59], v[192:195], v[180:183], v[56:59]
	v_mfma_f32_16x16x32_bf16 v[60:63], v[196:199], v[180:183], v[60:63]
	s_waitcnt vmcnt(0) lgkmcnt(0)
	s_barrier
	s_add_u32 m0, s56, 0x0
	s_nop 0
	global_load_lds_dwordx4 v236, s[24:25]
	s_add_u32 m0, s56, 0x400
	s_nop 0
	global_load_lds_dwordx4 v237, s[24:25]
	s_add_u32 m0, s56, 0x800
	s_nop 0
	global_load_lds_dwordx4 v238, s[24:25]
	s_add_u32 m0, s56, 0xc00
	s_nop 0
	global_load_lds_dwordx4 v239, s[24:25]
	s_add_u32 m0, s56, 0x4000
	s_nop 0
	global_load_lds_dwordx4 v244, s[26:27]
	s_add_u32 m0, s56, 0x4400
	s_nop 0
	global_load_lds_dwordx4 v245, s[26:27]
	s_add_u32 m0, s56, 0x4800
	s_nop 0
	global_load_lds_dwordx4 v246, s[26:27]
	s_add_u32 m0, s56, 0x4c00
	s_nop 0
	global_load_lds_dwordx4 v247, s[26:27]
	s_add_u32 s24, s24, 128
	s_addc_u32 s25, s25, 0
	s_add_u32 s26, s26, 128
	s_addc_u32 s27, s27, 0
	v_mfma_f32_16x16x32_bf16 v[0:3], v[216:219], v[200:203], v[0:3]
	ds_read_b128 v[168:171], v248 offset:32768
	v_mfma_f32_16x16x32_bf16 v[4:7], v[220:223], v[200:203], v[4:7]
	ds_read_b128 v[184:187], v250 offset:32768
	v_mfma_f32_16x16x32_bf16 v[8:11], v[228:231], v[200:203], v[8:11]
	ds_read_b128 v[172:175], v248 offset:34816
	v_mfma_f32_16x16x32_bf16 v[12:15], v[232:235], v[200:203], v[12:15]
	ds_read_b128 v[188:191], v250 offset:33280
	v_mfma_f32_16x16x32_bf16 v[16:19], v[216:219], v[204:207], v[16:19]
	ds_read_b128 v[176:179], v248 offset:36864
	v_mfma_f32_16x16x32_bf16 v[20:23], v[220:223], v[204:207], v[20:23]
	ds_read_b128 v[192:195], v250 offset:33792
	v_mfma_f32_16x16x32_bf16 v[24:27], v[228:231], v[204:207], v[24:27]
	ds_read_b128 v[180:183], v248 offset:38912
	v_mfma_f32_16x16x32_bf16 v[28:31], v[232:235], v[204:207], v[28:31]
	ds_read_b128 v[196:199], v250 offset:34304
	v_mfma_f32_16x16x32_bf16 v[32:35], v[216:219], v[208:211], v[32:35]
	v_mfma_f32_16x16x32_bf16 v[36:39], v[220:223], v[208:211], v[36:39]
	v_mfma_f32_16x16x32_bf16 v[40:43], v[228:231], v[208:211], v[40:43]
	v_mfma_f32_16x16x32_bf16 v[44:47], v[232:235], v[208:211], v[44:47]
	v_mfma_f32_16x16x32_bf16 v[48:51], v[216:219], v[212:215], v[48:51]
	v_mfma_f32_16x16x32_bf16 v[52:55], v[220:223], v[212:215], v[52:55]
	v_mfma_f32_16x16x32_bf16 v[56:59], v[228:231], v[212:215], v[56:59]
	v_mfma_f32_16x16x32_bf16 v[60:63], v[232:235], v[212:215], v[60:63]
	s_waitcnt lgkmcnt(0)
; template <int NI> ...
;     ...
;   for (int kt = 0; kt < nk; kt += 2) {
;     G_LOAD(a0, b0, min((kt + 2) * 32, klast));
;     G_COMPUTE(0);
;     G_WRITE(a1, b1, 1);
;     __syncthreads();
;     G_LOAD(a1, b1, min((kt + 3) * 32, klast));
;     G_COMPUTE(1);
;     G_WRITE(a0, b0, 0);
;     __syncthreads();
;   }
; __device__ void phase_merge4(CParams& p, int l, int tm, int tn, char* smem) {
;     ...
;     gemm_mainloop<4>(p.hbuf + (size_t)row0 * DM, DM,
;                      p.WgT + (((size_t)l * 4 + kb) * 1024 + col0) * 1024, 1024, 1024, sA, sB, acc, tid2);
	v_mfma_f32_16x16x32_bf16 v[0:3], v[184:187], v[168:171], v[0:3]
	ds_read_b128 v[200:203], v249 offset:32768
	v_mfma_f32_16x16x32_bf16 v[4:7], v[188:191], v[168:171], v[4:7]
	ds_read_b128 v[216:219], v251 offset:32768
	v_mfma_f32_16x16x32_bf16 v[8:11], v[192:195], v[168:171], v[8:11]
	ds_read_b128 v[204:207], v249 offset:34816
	v_mfma_f32_16x16x32_bf16 v[12:15], v[196:199], v[168:171], v[12:15]
	ds_read_b128 v[220:223], v251 offset:33280
	v_mfma_f32_16x16x32_bf16 v[16:19], v[184:187], v[172:175], v[16:19]
	ds_read_b128 v[208:211], v249 offset:36864
	v_mfma_f32_16x16x32_bf16 v[20:23], v[188:191], v[172:175], v[20:23]
	ds_read_b128 v[228:231], v251 offset:33792
	v_mfma_f32_16x16x32_bf16 v[24:27], v[192:195], v[172:175], v[24:27]
	ds_read_b128 v[212:215], v249 offset:38912
	v_mfma_f32_16x16x32_bf16 v[28:31], v[196:199], v[172:175], v[28:31]
	ds_read_b128 v[232:235], v251 offset:34304
	v_mfma_f32_16x16x32_bf16 v[32:35], v[184:187], v[176:179], v[32:35]
	v_mfma_f32_16x16x32_bf16 v[36:39], v[188:191], v[176:179], v[36:39]
	v_mfma_f32_16x16x32_bf16 v[40:43], v[192:195], v[176:179], v[40:43]
	v_mfma_f32_16x16x32_bf16 v[44:47], v[196:199], v[176:179], v[44:47]
	v_mfma_f32_16x16x32_bf16 v[48:51], v[184:187], v[180:183], v[48:51]
	v_mfma_f32_16x16x32_bf16 v[52:55], v[188:191], v[180:183], v[52:55]
	v_mfma_f32_16x16x32_bf16 v[56:59], v[192:195], v[180:183], v[56:59]
	v_mfma_f32_16x16x32_bf16 v[60:63], v[196:199], v[180:183], v[60:63]
	s_waitcnt vmcnt(0) lgkmcnt(0)
	s_barrier
	s_add_u32 m0, s56, 0x8000
	s_nop 0
	global_load_lds_dwordx4 v236, s[24:25]
	s_add_u32 m0, s56, 0x8400
	s_nop 0
	global_load_lds_dwordx4 v237, s[24:25]
	s_add_u32 m0, s56, 0x8800
	s_nop 0
	global_load_lds_dwordx4 v238, s[24:25]
	s_add_u32 m0, s56, 0x8c00
	s_nop 0
	global_load_lds_dwordx4 v239, s[24:25]
	s_add_u32 m0, s56, 0xc000
	s_nop 0
	global_load_lds_dwordx4 v244, s[26:27]
	s_add_u32 m0, s56, 0xc400
	s_nop 0
	global_load_lds_dwordx4 v245, s[26:27]
	s_add_u32 m0, s56, 0xc800
	s_nop 0
	global_load_lds_dwordx4 v246, s[26:27]
	s_add_u32 m0, s56, 0xcc00
	s_nop 0
	global_load_lds_dwordx4 v247, s[26:27]
	s_add_u32 s24, s24, 128
	s_addc_u32 s25, s25, 0
	s_add_u32 s26, s26, 128
	s_addc_u32 s27, s27, 0
	v_mfma_f32_16x16x32_bf16 v[0:3], v[216:219], v[200:203], v[0:3]
	ds_read_b128 v[168:171], v248 offset:0
	v_mfma_f32_16x16x32_bf16 v[4:7], v[220:223], v[200:203], v[4:7]
	ds_read_b128 v[184:187], v250 offset:0
	v_mfma_f32_16x16x32_bf16 v[8:11], v[228:231], v[200:203], v[8:11]
	ds_read_b128 v[172:175], v248 offset:2048
	v_mfma_f32_16x16x32_bf16 v[12:15], v[232:235], v[200:203], v[12:15]
	ds_read_b128 v[188:191], v250 offset:512
	v_mfma_f32_16x16x32_bf16 v[16:19], v[216:219], v[204:207], v[16:19]
	ds_read_b128 v[176:179], v248 offset:4096
	v_mfma_f32_16x16x32_bf16 v[20:23], v[220:223], v[204:207], v[20:23]
	ds_read_b128 v[192:195], v250 offset:1024
	v_mfma_f32_16x16x32_bf16 v[24:27], v[228:231], v[204:207], v[24:27]
	ds_read_b128 v[180:183], v248 offset:6144
	v_mfma_f32_16x16x32_bf16 v[28:31], v[232:235], v[204:207], v[28:31]
	ds_read_b128 v[196:199], v250 offset:1536
	v_mfma_f32_16x16x32_bf16 v[32:35], v[216:219], v[208:211], v[32:35]
	v_mfma_f32_16x16x32_bf16 v[36:39], v[220:223], v[208:211], v[36:39]
	v_mfma_f32_16x16x32_bf16 v[40:43], v[228:231], v[208:211], v[40:43]
	v_mfma_f32_16x16x32_bf16 v[44:47], v[232:235], v[208:211], v[44:47]
	v_mfma_f32_16x16x32_bf16 v[48:51], v[216:219], v[212:215], v[48:51]
	v_mfma_f32_16x16x32_bf16 v[52:55], v[220:223], v[212:215], v[52:55]
	v_mfma_f32_16x16x32_bf16 v[56:59], v[228:231], v[212:215], v[56:59]
	v_mfma_f32_16x16x32_bf16 v[60:63], v[232:235], v[212:215], v[60:63]
	s_waitcnt lgkmcnt(0)
	v_mfma_f32_16x16x32_bf16 v[0:3], v[184:187], v[168:171], v[0:3]
	ds_read_b128 v[200:203], v249 offset:0
	v_mfma_f32_16x16x32_bf16 v[4:7], v[188:191], v[168:171], v[4:7]
	ds_read_b128 v[216:219], v251 offset:0
	v_mfma_f32_16x16x32_bf16 v[8:11], v[192:195], v[168:171], v[8:11]
	ds_read_b128 v[204:207], v249 offset:2048
	v_mfma_f32_16x16x32_bf16 v[12:15], v[196:199], v[168:171], v[12:15]
	ds_read_b128 v[220:223], v251 offset:512
	v_mfma_f32_16x16x32_bf16 v[16:19], v[184:187], v[172:175], v[16:19]
	ds_read_b128 v[208:211], v249 offset:4096
	v_mfma_f32_16x16x32_bf16 v[20:23], v[188:191], v[172:175], v[20:23]
	ds_read_b128 v[228:231], v251 offset:1024
	v_mfma_f32_16x16x32_bf16 v[24:27], v[192:195], v[172:175], v[24:27]
	ds_read_b128 v[212:215], v249 offset:6144
	v_mfma_f32_16x16x32_bf16 v[28:31], v[196:199], v[172:175], v[28:31]
	ds_read_b128 v[232:235], v251 offset:1536
	v_mfma_f32_16x16x32_bf16 v[32:35], v[184:187], v[176:179], v[32:35]
	v_mfma_f32_16x16x32_bf16 v[36:39], v[188:191], v[176:179], v[36:39]
	v_mfma_f32_16x16x32_bf16 v[40:43], v[192:195], v[176:179], v[40:43]
	v_mfma_f32_16x16x32_bf16 v[44:47], v[196:199], v[176:179], v[44:47]
	v_mfma_f32_16x16x32_bf16 v[48:51], v[184:187], v[180:183], v[48:51]
	v_mfma_f32_16x16x32_bf16 v[52:55], v[188:191], v[180:183], v[52:55]
	v_mfma_f32_16x16x32_bf16 v[56:59], v[192:195], v[180:183], v[56:59]
	v_mfma_f32_16x16x32_bf16 v[60:63], v[196:199], v[180:183], v[60:63]
	s_waitcnt vmcnt(0) lgkmcnt(0)
	s_barrier
; template <int NI> ...
;     ...
;   for (int kt = 0; kt < nk; kt += 2) {
;     G_LOAD(a0, b0, min((kt + 2) * 32, klast));
;     G_COMPUTE(0);
;     G_WRITE(a1, b1, 1);
;     __syncthreads();
;     G_LOAD(a1, b1, min((kt + 3) * 32, klast));
;     G_COMPUTE(1);
;     G_WRITE(a0, b0, 0);
;     __syncthreads();
;   }
; __device__ void phase_merge4(CParams& p, int l, int tm, int tn, char* smem) {
;     ...
;     gemm_mainloop<4>(p.hbuf + (size_t)row0 * DM, DM,
;                      p.WgT + (((size_t)l * 4 + kb) * 1024 + col0) * 1024, 1024, 1024, sA, sB, acc, tid2);
	s_add_u32 m0, s56, 0x0
	s_nop 0
	global_load_lds_dwordx4 v236, s[24:25]
	s_add_u32 m0, s56, 0x400
	s_nop 0
	global_load_lds_dwordx4 v237, s[24:25]
	s_add_u32 m0, s56, 0x800
	s_nop 0
	global_load_lds_dwordx4 v238, s[24:25]
	s_add_u32 m0, s56, 0xc00
	s_nop 0
	global_load_lds_dwordx4 v239, s[24:25]
	s_add_u32 m0, s56, 0x4000
	s_nop 0
	global_load_lds_dwordx4 v244, s[26:27]
	s_add_u32 m0, s56, 0x4400
	s_nop 0
	global_load_lds_dwordx4 v245, s[26:27]
	s_add_u32 m0, s56, 0x4800
	s_nop 0
	global_load_lds_dwordx4 v246, s[26:27]
	s_add_u32 m0, s56, 0x4c00
	s_nop 0
	global_load_lds_dwordx4 v247, s[26:27]
	s_add_u32 s24, s24, 128
	s_addc_u32 s25, s25, 0
	s_add_u32 s26, s26, 128
	s_addc_u32 s27, s27, 0
	v_mfma_f32_16x16x32_bf16 v[0:3], v[216:219], v[200:203], v[0:3]
	ds_read_b128 v[168:171], v248 offset:32768
	v_mfma_f32_16x16x32_bf16 v[4:7], v[220:223], v[200:203], v[4:7]
	ds_read_b128 v[184:187], v250 offset:32768
	v_mfma_f32_16x16x32_bf16 v[8:11], v[228:231], v[200:203], v[8:11]
	ds_read_b128 v[172:175], v248 offset:34816
	v_mfma_f32_16x16x32_bf16 v[12:15], v[232:235], v[200:203], v[12:15]
	ds_read_b128 v[188:191], v250 offset:33280
	v_mfma_f32_16x16x32_bf16 v[16:19], v[216:219], v[204:207], v[16:19]
	ds_read_b128 v[176:179], v248 offset:36864
	v_mfma_f32_16x16x32_bf16 v[20:23], v[220:223], v[204:207], v[20:23]
	ds_read_b128 v[192:195], v250 offset:33792
	v_mfma_f32_16x16x32_bf16 v[24:27], v[228:231], v[204:207], v[24:27]
	ds_read_b128 v[180:183], v248 offset:38912
	v_mfma_f32_16x16x32_bf16 v[28:31], v[232:235], v[204:207], v[28:31]
	ds_read_b128 v[196:199], v250 offset:34304
	v_mfma_f32_16x16x32_bf16 v[32:35], v[216:219], v[208:211], v[32:35]
	v_mfma_f32_16x16x32_bf16 v[36:39], v[220:223], v[208:211], v[36:39]
	v_mfma_f32_16x16x32_bf16 v[40:43], v[228:231], v[208:211], v[40:43]
	v_mfma_f32_16x16x32_bf16 v[44:47], v[232:235], v[208:211], v[44:47]
	v_mfma_f32_16x16x32_bf16 v[48:51], v[216:219], v[212:215], v[48:51]
	v_mfma_f32_16x16x32_bf16 v[52:55], v[220:223], v[212:215], v[52:55]
	v_mfma_f32_16x16x32_bf16 v[56:59], v[228:231], v[212:215], v[56:59]
	v_mfma_f32_16x16x32_bf16 v[60:63], v[232:235], v[212:215], v[60:63]
	s_waitcnt lgkmcnt(0)
	v_mfma_f32_16x16x32_bf16 v[0:3], v[184:187], v[168:171], v[0:3]
	ds_read_b128 v[200:203], v249 offset:32768
	v_mfma_f32_16x16x32_bf16 v[4:7], v[188:191], v[168:171], v[4:7]
	ds_read_b128 v[216:219], v251 offset:32768
	v_mfma_f32_16x16x32_bf16 v[8:11], v[192:195], v[168:171], v[8:11]
	ds_read_b128 v[204:207], v249 offset:34816
	v_mfma_f32_16x16x32_bf16 v[12:15], v[196:199], v[168:171], v[12:15]
	ds_read_b128 v[220:223], v251 offset:33280
	v_mfma_f32_16x16x32_bf16 v[16:19], v[184:187], v[172:175], v[16:19]
	ds_read_b128 v[208:211], v249 offset:36864
	v_mfma_f32_16x16x32_bf16 v[20:23], v[188:191], v[172:175], v[20:23]
	ds_read_b128 v[228:231], v251 offset:33792
	v_mfma_f32_16x16x32_bf16 v[24:27], v[192:195], v[172:175], v[24:27]
	ds_read_b128 v[212:215], v249 offset:38912
	v_mfma_f32_16x16x32_bf16 v[28:31], v[196:199], v[172:175], v[28:31]
	ds_read_b128 v[232:235], v251 offset:34304
	v_mfma_f32_16x16x32_bf16 v[32:35], v[184:187], v[176:179], v[32:35]
	v_mfma_f32_16x16x32_bf16 v[36:39], v[188:191], v[176:179], v[36:39]
	v_mfma_f32_16x16x32_bf16 v[40:43], v[192:195], v[176:179], v[40:43]
	v_mfma_f32_16x16x32_bf16 v[44:47], v[196:199], v[176:179], v[44:47]
	v_mfma_f32_16x16x32_bf16 v[48:51], v[184:187], v[180:183], v[48:51]
	v_mfma_f32_16x16x32_bf16 v[52:55], v[188:191], v[180:183], v[52:55]
	v_mfma_f32_16x16x32_bf16 v[56:59], v[192:195], v[180:183], v[56:59]
	v_mfma_f32_16x16x32_bf16 v[60:63], v[196:199], v[180:183], v[60:63]
	s_waitcnt vmcnt(0) lgkmcnt(0)
	s_barrier
	s_add_u32 m0, s56, 0x8000
	s_nop 0
	global_load_lds_dwordx4 v236, s[24:25]
	s_add_u32 m0, s56, 0x8400
	s_nop 0
	global_load_lds_dwordx4 v237, s[24:25]
	s_add_u32 m0, s56, 0x8800
	s_nop 0
	global_load_lds_dwordx4 v238, s[24:25]
	s_add_u32 m0, s56, 0x8c00
	s_nop 0
	global_load_lds_dwordx4 v239, s[24:25]
	s_add_u32 m0, s56, 0xc000
	s_nop 0
	global_load_lds_dwordx4 v244, s[26:27]
	s_add_u32 m0, s56, 0xc400
	s_nop 0
	global_load_lds_dwordx4 v245, s[26:27]
	s_add_u32 m0, s56, 0xc800
	s_nop 0
	global_load_lds_dwordx4 v246, s[26:27]
	s_add_u32 m0, s56, 0xcc00
	s_nop 0
	global_load_lds_dwordx4 v247, s[26:27]
	s_add_u32 s24, s24, 128
	s_addc_u32 s25, s25, 0
	s_add_u32 s26, s26, 128
	s_addc_u32 s27, s27, 0
	v_mfma_f32_16x16x32_bf16 v[0:3], v[216:219], v[200:203], v[0:3]
	ds_read_b128 v[168:171], v248 offset:0
	v_mfma_f32_16x16x32_bf16 v[4:7], v[220:223], v[200:203], v[4:7]
	ds_read_b128 v[184:187], v250 offset:0
	v_mfma_f32_16x16x32_bf16 v[8:11], v[228:231], v[200:203], v[8:11]
	ds_read_b128 v[172:175], v248 offset:2048
	v_mfma_f32_16x16x32_bf16 v[12:15], v[232:235], v[200:203], v[12:15]
	ds_read_b128 v[188:191], v250 offset:512
	v_mfma_f32_16x16x32_bf16 v[16:19], v[216:219], v[204:207], v[16:19]
	ds_read_b128 v[176:179], v248 offset:4096
	v_mfma_f32_16x16x32_bf16 v[20:23], v[220:223], v[204:207], v[20:23]
	ds_read_b128 v[192:195], v250 offset:1024
	v_mfma_f32_16x16x32_bf16 v[24:27], v[228:231], v[204:207], v[24:27]
	ds_read_b128 v[180:183], v248 offset:6144
	v_mfma_f32_16x16x32_bf16 v[28:31], v[232:235], v[204:207], v[28:31]
	ds_read_b128 v[196:199], v250 offset:1536
	v_mfma_f32_16x16x32_bf16 v[32:35], v[216:219], v[208:211], v[32:35]
	v_mfma_f32_16x16x32_bf16 v[36:39], v[220:223], v[208:211], v[36:39]
	v_mfma_f32_16x16x32_bf16 v[40:43], v[228:231], v[208:211], v[40:43]
	v_mfma_f32_16x16x32_bf16 v[44:47], v[232:235], v[208:211], v[44:47]
	v_mfma_f32_16x16x32_bf16 v[48:51], v[216:219], v[212:215], v[48:51]
	v_mfma_f32_16x16x32_bf16 v[52:55], v[220:223], v[212:215], v[52:55]
	v_mfma_f32_16x16x32_bf16 v[56:59], v[228:231], v[212:215], v[56:59]
	v_mfma_f32_16x16x32_bf16 v[60:63], v[232:235], v[212:215], v[60:63]
	s_waitcnt lgkmcnt(0)
; template <int NI> ...
;     ...
;   for (int kt = 0; kt < nk; kt += 2) {
;     G_LOAD(a0, b0, min((kt + 2) * 32, klast));
;     G_COMPUTE(0);
;     G_WRITE(a1, b1, 1);
;     __syncthreads();
;     G_LOAD(a1, b1, min((kt + 3) * 32, klast));
;     G_COMPUTE(1);
;     G_WRITE(a0, b0, 0);
;     __syncthreads();
;   }
; __device__ void phase_merge4(CParams& p, int l, int tm, int tn, char* smem) {
;     ...
;   for (int kb0 = 0; kb0 < 4; kb0++) {
;     int kb = kb0;
;     asm volatile("" : "+s"(kb));
;     int tid2 = tid;
;     asm volatile("" : "+v"(tid2));
;     unsigned pk[4][4][2];
;     {
;       f32x4 acc[4][4];
;       zero_acc<4>(acc);
;       gemm_mainloop<4>(p.br + (size_t)row0 * 1024 + kb * 256, 1024,
;                        p.WbT + (((size_t)l * 4 + kb) * 1024 + col0) * 256, 256, 256, sA, sB, acc, tid2);
	v_mfma_f32_16x16x32_bf16 v[0:3], v[184:187], v[168:171], v[0:3]
	ds_read_b128 v[200:203], v249 offset:0
	v_mfma_f32_16x16x32_bf16 v[4:7], v[188:191], v[168:171], v[4:7]
	ds_read_b128 v[216:219], v251 offset:0
	v_mfma_f32_16x16x32_bf16 v[8:11], v[192:195], v[168:171], v[8:11]
	ds_read_b128 v[204:207], v249 offset:2048
	v_mfma_f32_16x16x32_bf16 v[12:15], v[196:199], v[168:171], v[12:15]
	ds_read_b128 v[220:223], v251 offset:512
	v_mfma_f32_16x16x32_bf16 v[16:19], v[184:187], v[172:175], v[16:19]
	ds_read_b128 v[208:211], v249 offset:4096
	v_mfma_f32_16x16x32_bf16 v[20:23], v[188:191], v[172:175], v[20:23]
	ds_read_b128 v[228:231], v251 offset:1024
	v_mfma_f32_16x16x32_bf16 v[24:27], v[192:195], v[172:175], v[24:27]
	ds_read_b128 v[212:215], v249 offset:6144
	v_mfma_f32_16x16x32_bf16 v[28:31], v[196:199], v[172:175], v[28:31]
	ds_read_b128 v[232:235], v251 offset:1536
	v_mfma_f32_16x16x32_bf16 v[32:35], v[184:187], v[176:179], v[32:35]
	v_mfma_f32_16x16x32_bf16 v[36:39], v[188:191], v[176:179], v[36:39]
	v_mfma_f32_16x16x32_bf16 v[40:43], v[192:195], v[176:179], v[40:43]
	v_mfma_f32_16x16x32_bf16 v[44:47], v[196:199], v[176:179], v[44:47]
	v_mfma_f32_16x16x32_bf16 v[48:51], v[184:187], v[180:183], v[48:51]
	v_mfma_f32_16x16x32_bf16 v[52:55], v[188:191], v[180:183], v[52:55]
	v_mfma_f32_16x16x32_bf16 v[56:59], v[192:195], v[180:183], v[56:59]
	v_mfma_f32_16x16x32_bf16 v[60:63], v[196:199], v[180:183], v[60:63]
	s_waitcnt vmcnt(0) lgkmcnt(0)
	s_barrier
	s_mov_b64 s[24:25], s[28:29]
	s_mov_b64 s[26:27], s[44:45]
	s_add_u32 m0, s56, 0x0
	s_nop 0
	global_load_lds_dwordx4 v236, s[24:25]
	s_add_u32 m0, s56, 0x400
	s_nop 0
	global_load_lds_dwordx4 v237, s[24:25]
	s_add_u32 m0, s56, 0x800
	s_nop 0
	global_load_lds_dwordx4 v238, s[24:25]
	s_add_u32 m0, s56, 0xc00
	s_nop 0
	global_load_lds_dwordx4 v239, s[24:25]
	s_add_u32 m0, s56, 0x4000
	s_nop 0
	global_load_lds_dwordx4 v240, s[26:27]
	s_add_u32 m0, s56, 0x4400
	s_nop 0
	global_load_lds_dwordx4 v241, s[26:27]
	s_add_u32 m0, s56, 0x4800
	s_nop 0
	global_load_lds_dwordx4 v242, s[26:27]
	s_add_u32 m0, s56, 0x4c00
	s_nop 0
	global_load_lds_dwordx4 v243, s[26:27]
	s_add_u32 s24, s24, 128
	s_addc_u32 s25, s25, 0
	s_add_u32 s26, s26, 128
	s_addc_u32 s27, s27, 0
	v_mfma_f32_16x16x32_bf16 v[0:3], v[216:219], v[200:203], v[0:3]
	ds_read_b128 v[168:171], v248 offset:32768
	v_mfma_f32_16x16x32_bf16 v[4:7], v[220:223], v[200:203], v[4:7]
	ds_read_b128 v[184:187], v250 offset:32768
	v_mfma_f32_16x16x32_bf16 v[8:11], v[228:231], v[200:203], v[8:11]
	ds_read_b128 v[172:175], v248 offset:34816
	v_mfma_f32_16x16x32_bf16 v[12:15], v[232:235], v[200:203], v[12:15]
	ds_read_b128 v[188:191], v250 offset:33280
	v_mfma_f32_16x16x32_bf16 v[16:19], v[216:219], v[204:207], v[16:19]
	ds_read_b128 v[176:179], v248 offset:36864
	v_mfma_f32_16x16x32_bf16 v[20:23], v[220:223], v[204:207], v[20:23]
	ds_read_b128 v[192:195], v250 offset:33792
	v_mfma_f32_16x16x32_bf16 v[24:27], v[228:231], v[204:207], v[24:27]
	ds_read_b128 v[180:183], v248 offset:38912
	v_mfma_f32_16x16x32_bf16 v[28:31], v[232:235], v[204:207], v[28:31]
	ds_read_b128 v[196:199], v250 offset:34304
	v_mfma_f32_16x16x32_bf16 v[32:35], v[216:219], v[208:211], v[32:35]
	v_mfma_f32_16x16x32_bf16 v[36:39], v[220:223], v[208:211], v[36:39]
	v_mfma_f32_16x16x32_bf16 v[40:43], v[228:231], v[208:211], v[40:43]
	v_mfma_f32_16x16x32_bf16 v[44:47], v[232:235], v[208:211], v[44:47]
	v_mfma_f32_16x16x32_bf16 v[48:51], v[216:219], v[212:215], v[48:51]
	v_mfma_f32_16x16x32_bf16 v[52:55], v[220:223], v[212:215], v[52:55]
	v_mfma_f32_16x16x32_bf16 v[56:59], v[228:231], v[212:215], v[56:59]
	v_mfma_f32_16x16x32_bf16 v[60:63], v[232:235], v[212:215], v[60:63]
	s_waitcnt lgkmcnt(0)
	v_mfma_f32_16x16x32_bf16 v[0:3], v[184:187], v[168:171], v[0:3]
	ds_read_b128 v[200:203], v249 offset:32768
	v_mfma_f32_16x16x32_bf16 v[4:7], v[188:191], v[168:171], v[4:7]
	ds_read_b128 v[216:219], v251 offset:32768
	v_mfma_f32_16x16x32_bf16 v[8:11], v[192:195], v[168:171], v[8:11]
	ds_read_b128 v[204:207], v249 offset:34816
	v_mfma_f32_16x16x32_bf16 v[12:15], v[196:199], v[168:171], v[12:15]
	ds_read_b128 v[220:223], v251 offset:33280
	v_mfma_f32_16x16x32_bf16 v[16:19], v[184:187], v[172:175], v[16:19]
	ds_read_b128 v[208:211], v249 offset:36864
	v_mfma_f32_16x16x32_bf16 v[20:23], v[188:191], v[172:175], v[20:23]
	ds_read_b128 v[228:231], v251 offset:33792
	v_mfma_f32_16x16x32_bf16 v[24:27], v[192:195], v[172:175], v[24:27]
	ds_read_b128 v[212:215], v249 offset:38912
	v_mfma_f32_16x16x32_bf16 v[28:31], v[196:199], v[172:175], v[28:31]
	ds_read_b128 v[232:235], v251 offset:34304
	v_mfma_f32_16x16x32_bf16 v[32:35], v[184:187], v[176:179], v[32:35]
	v_mfma_f32_16x16x32_bf16 v[36:39], v[188:191], v[176:179], v[36:39]
	v_mfma_f32_16x16x32_bf16 v[40:43], v[192:195], v[176:179], v[40:43]
	v_mfma_f32_16x16x32_bf16 v[44:47], v[196:199], v[176:179], v[44:47]
	v_mfma_f32_16x16x32_bf16 v[48:51], v[184:187], v[180:183], v[48:51]
	v_mfma_f32_16x16x32_bf16 v[52:55], v[188:191], v[180:183], v[52:55]
	v_mfma_f32_16x16x32_bf16 v[56:59], v[192:195], v[180:183], v[56:59]
	v_mfma_f32_16x16x32_bf16 v[60:63], v[196:199], v[180:183], v[60:63]
	s_waitcnt vmcnt(0) lgkmcnt(0)
	s_barrier
; __device__ __forceinline__ float sigmoidf_(float v) { return 1.f / (1.f + __expf(-v)); }
; template <int NI> ...
;     ...
;   for (int kt = 0; kt < nk; kt += 2) {
;     G_LOAD(a0, b0, min((kt + 2) * 32, klast));
;     G_COMPUTE(0);
;     G_WRITE(a1, b1, 1);
;     __syncthreads();
;     G_LOAD(a1, b1, min((kt + 3) * 32, klast));
;     G_COMPUTE(1);
;     G_WRITE(a0, b0, 0);
;     __syncthreads();
;   }
; __device__ void phase_merge4(CParams& p, int l, int tm, int tn, char* smem) {
;     ...
; #pragma unroll
;     for (int mi = 0; mi < 4; mi++)
; #pragma unroll
;       for (int ni = 0; ni < 4; ni++) {
;         unsigned p0 = pk[mi][ni][0], p1 = pk[mi][ni][1], m0 = mer[mi][ni][0], m1 = mer[mi][ni][1];
;         float r0 = __uint_as_float(m0 << 16) + sigmoidf_(acc[mi][ni][0]) * __uint_as_float(p0 << 16);
;         float r1 = __uint_as_float(m0 & 0xffff0000u) + sigmoidf_(acc[mi][ni][1]) * __uint_as_float(p0 & 0xffff0000u);
;         float r2 = __uint_as_float(m1 << 16) + sigmoidf_(acc[mi][ni][2]) * __uint_as_float(p1 << 16);
;         float r3 = __uint_as_float(m1 & 0xffff0000u) + sigmoidf_(acc[mi][ni][3]) * __uint_as_float(p1 & 0xffff0000u);
	s_add_u32 m0, s56, 0x8000
	s_nop 0
	global_load_lds_dwordx4 v236, s[24:25]
	s_add_u32 m0, s56, 0x8400
	s_nop 0
	global_load_lds_dwordx4 v237, s[24:25]
	s_add_u32 m0, s56, 0x8800
	s_nop 0
	global_load_lds_dwordx4 v238, s[24:25]
	s_add_u32 m0, s56, 0x8c00
	s_nop 0
	global_load_lds_dwordx4 v239, s[24:25]
	s_add_u32 m0, s56, 0xc000
	s_nop 0
	global_load_lds_dwordx4 v240, s[26:27]
	s_add_u32 m0, s56, 0xc400
	s_nop 0
	global_load_lds_dwordx4 v241, s[26:27]
	s_add_u32 m0, s56, 0xc800
	s_nop 0
	global_load_lds_dwordx4 v242, s[26:27]
	s_add_u32 m0, s56, 0xcc00
	s_nop 0
	global_load_lds_dwordx4 v243, s[26:27]
	s_add_u32 s24, s24, 128
	s_addc_u32 s25, s25, 0
	s_add_u32 s26, s26, 128
	s_addc_u32 s27, s27, 0
	v_mfma_f32_16x16x32_bf16 v[0:3], v[216:219], v[200:203], v[0:3]
	ds_read_b128 v[168:171], v248 offset:0
	v_mfma_f32_16x16x32_bf16 v[4:7], v[220:223], v[200:203], v[4:7]
	ds_read_b128 v[184:187], v250 offset:0
	v_mfma_f32_16x16x32_bf16 v[8:11], v[228:231], v[200:203], v[8:11]
	ds_read_b128 v[172:175], v248 offset:2048
	v_mfma_f32_16x16x32_bf16 v[12:15], v[232:235], v[200:203], v[12:15]
	ds_read_b128 v[188:191], v250 offset:512
	v_mfma_f32_16x16x32_bf16 v[16:19], v[216:219], v[204:207], v[16:19]
	ds_read_b128 v[176:179], v248 offset:4096
	v_mfma_f32_16x16x32_bf16 v[20:23], v[220:223], v[204:207], v[20:23]
	ds_read_b128 v[192:195], v250 offset:1024
	v_mfma_f32_16x16x32_bf16 v[24:27], v[228:231], v[204:207], v[24:27]
	ds_read_b128 v[180:183], v248 offset:6144
	v_mfma_f32_16x16x32_bf16 v[28:31], v[232:235], v[204:207], v[28:31]
	ds_read_b128 v[196:199], v250 offset:1536
	v_mfma_f32_16x16x32_bf16 v[32:35], v[216:219], v[208:211], v[32:35]
	v_mfma_f32_16x16x32_bf16 v[36:39], v[220:223], v[208:211], v[36:39]
	v_mfma_f32_16x16x32_bf16 v[40:43], v[228:231], v[208:211], v[40:43]
	v_mfma_f32_16x16x32_bf16 v[44:47], v[232:235], v[208:211], v[44:47]
	v_mfma_f32_16x16x32_bf16 v[48:51], v[216:219], v[212:215], v[48:51]
	v_mfma_f32_16x16x32_bf16 v[52:55], v[220:223], v[212:215], v[52:55]
	v_mfma_f32_16x16x32_bf16 v[56:59], v[228:231], v[212:215], v[56:59]
	v_mfma_f32_16x16x32_bf16 v[60:63], v[232:235], v[212:215], v[60:63]
	s_nop 15
	s_nop 7
	v_mul_f32_e32 v200, 0xbfb8aa3b, v0
	v_mul_f32_e32 v201, 0xbfb8aa3b, v1
	v_mul_f32_e32 v202, 0xbfb8aa3b, v2
	v_mul_f32_e32 v203, 0xbfb8aa3b, v3
	v_mul_f32_e32 v204, 0xbfb8aa3b, v4
	v_mul_f32_e32 v205, 0xbfb8aa3b, v5
	v_mul_f32_e32 v206, 0xbfb8aa3b, v6
	v_mul_f32_e32 v207, 0xbfb8aa3b, v7
	v_exp_f32_e32 v200, v200
	v_exp_f32_e32 v201, v201
	v_exp_f32_e32 v202, v202
	v_exp_f32_e32 v203, v203
	v_exp_f32_e32 v204, v204
	v_exp_f32_e32 v205, v205
	v_exp_f32_e32 v206, v206
	v_exp_f32_e32 v207, v207
	v_add_f32_e32 v200, 1.0, v200
	v_add_f32_e32 v201, 1.0, v201
	v_add_f32_e32 v202, 1.0, v202
	v_add_f32_e32 v203, 1.0, v203
	v_add_f32_e32 v204, 1.0, v204
	v_add_f32_e32 v205, 1.0, v205
	v_add_f32_e32 v206, 1.0, v206
	v_add_f32_e32 v207, 1.0, v207
	v_rcp_f32_e32 v200, v200
	v_rcp_f32_e32 v201, v201
	v_rcp_f32_e32 v202, v202
	v_rcp_f32_e32 v203, v203
	v_rcp_f32_e32 v204, v204
	v_rcp_f32_e32 v205, v205
	v_rcp_f32_e32 v206, v206
	v_rcp_f32_e32 v207, v207
	v_lshlrev_b32_e32 v208, 16, v128
	v_and_b32_e32 v209, 0xffff0000, v128
	v_lshlrev_b32_e32 v210, 16, v129
	v_and_b32_e32 v211, 0xffff0000, v129
	v_lshlrev_b32_e32 v212, 16, v130
	v_and_b32_e32 v213, 0xffff0000, v130
	v_lshlrev_b32_e32 v214, 16, v131
	v_and_b32_e32 v215, 0xffff0000, v131
	v_fmac_f32_e32 v64, v200, v208
	v_fmac_f32_e32 v65, v201, v209
	v_fmac_f32_e32 v66, v202, v210
	v_fmac_f32_e32 v67, v203, v211
	v_fmac_f32_e32 v68, v204, v212
	v_fmac_f32_e32 v69, v205, v213
	v_fmac_f32_e32 v70, v206, v214
	v_fmac_f32_e32 v71, v207, v215
	v_mul_f32_e32 v200, 0xbfb8aa3b, v8
	v_mul_f32_e32 v201, 0xbfb8aa3b, v9
	v_mul_f32_e32 v202, 0xbfb8aa3b, v10
	v_mul_f32_e32 v203, 0xbfb8aa3b, v11
	v_mul_f32_e32 v204, 0xbfb8aa3b, v12
	v_mul_f32_e32 v205, 0xbfb8aa3b, v13
	v_mul_f32_e32 v206, 0xbfb8aa3b, v14
	v_mul_f32_e32 v207, 0xbfb8aa3b, v15
	v_exp_f32_e32 v200, v200
	v_exp_f32_e32 v201, v201
	v_exp_f32_e32 v202, v202
	v_exp_f32_e32 v203, v203
	v_exp_f32_e32 v204, v204
	v_exp_f32_e32 v205, v205
	v_exp_f32_e32 v206, v206
	v_exp_f32_e32 v207, v207
	v_add_f32_e32 v200, 1.0, v200
	v_add_f32_e32 v201, 1.0, v201
	v_add_f32_e32 v202, 1.0, v202
	v_add_f32_e32 v203, 1.0, v203
	v_add_f32_e32 v204, 1.0, v204
	v_add_f32_e32 v205, 1.0, v205
	v_add_f32_e32 v206, 1.0, v206
	v_add_f32_e32 v207, 1.0, v207
	v_rcp_f32_e32 v200, v200
	v_rcp_f32_e32 v201, v201
	v_rcp_f32_e32 v202, v202
	v_rcp_f32_e32 v203, v203
	v_rcp_f32_e32 v204, v204
	v_rcp_f32_e32 v205, v205
	v_rcp_f32_e32 v206, v206
	v_rcp_f32_e32 v207, v207
	v_lshlrev_b32_e32 v208, 16, v132
	v_and_b32_e32 v209, 0xffff0000, v132
	v_lshlrev_b32_e32 v210, 16, v133
	v_and_b32_e32 v211, 0xffff0000, v133
	v_lshlrev_b32_e32 v212, 16, v134
	v_and_b32_e32 v213, 0xffff0000, v134
	v_lshlrev_b32_e32 v214, 16, v135
	v_and_b32_e32 v215, 0xffff0000, v135
	v_fmac_f32_e32 v72, v200, v208
	v_fmac_f32_e32 v73, v201, v209
	v_fmac_f32_e32 v74, v202, v210
	v_fmac_f32_e32 v75, v203, v211
	v_fmac_f32_e32 v76, v204, v212
	v_fmac_f32_e32 v77, v205, v213
	v_fmac_f32_e32 v78, v206, v214
	v_fmac_f32_e32 v79, v207, v215
	v_mul_f32_e32 v200, 0xbfb8aa3b, v16
	v_mul_f32_e32 v201, 0xbfb8aa3b, v17
	v_mul_f32_e32 v202, 0xbfb8aa3b, v18
	v_mul_f32_e32 v203, 0xbfb8aa3b, v19
	v_mul_f32_e32 v204, 0xbfb8aa3b, v20
	v_mul_f32_e32 v205, 0xbfb8aa3b, v21
	v_mul_f32_e32 v206, 0xbfb8aa3b, v22
	v_mul_f32_e32 v207, 0xbfb8aa3b, v23
	v_exp_f32_e32 v200, v200
	v_exp_f32_e32 v201, v201
	v_exp_f32_e32 v202, v202
	v_exp_f32_e32 v203, v203
	v_exp_f32_e32 v204, v204
	v_exp_f32_e32 v205, v205
	v_exp_f32_e32 v206, v206
; __device__ __forceinline__ float sigmoidf_(float v) { return 1.f / (1.f + __expf(-v)); }
; __device__ void phase_merge4(CParams& p, int l, int tm, int tn, char* smem) {
;     ...
; #pragma unroll
;     for (int mi = 0; mi < 4; mi++)
; #pragma unroll
;       for (int ni = 0; ni < 4; ni++) {
;         unsigned p0 = pk[mi][ni][0], p1 = pk[mi][ni][1], m0 = mer[mi][ni][0], m1 = mer[mi][ni][1];
;         float r0 = __uint_as_float(m0 << 16) + sigmoidf_(acc[mi][ni][0]) * __uint_as_float(p0 << 16);
;         float r1 = __uint_as_float(m0 & 0xffff0000u) + sigmoidf_(acc[mi][ni][1]) * __uint_as_float(p0 & 0xffff0000u);
;         float r2 = __uint_as_float(m1 << 16) + sigmoidf_(acc[mi][ni][2]) * __uint_as_float(p1 << 16);
;         float r3 = __uint_as_float(m1 & 0xffff0000u) + sigmoidf_(acc[mi][ni][3]) * __uint_as_float(p1 & 0xffff0000u);
	v_exp_f32_e32 v207, v207
	v_add_f32_e32 v200, 1.0, v200
	v_add_f32_e32 v201, 1.0, v201
	v_add_f32_e32 v202, 1.0, v202
	v_add_f32_e32 v203, 1.0, v203
	v_add_f32_e32 v204, 1.0, v204
	v_add_f32_e32 v205, 1.0, v205
	v_add_f32_e32 v206, 1.0, v206
	v_add_f32_e32 v207, 1.0, v207
	v_rcp_f32_e32 v200, v200
	v_rcp_f32_e32 v201, v201
	v_rcp_f32_e32 v202, v202
	v_rcp_f32_e32 v203, v203
	v_rcp_f32_e32 v204, v204
	v_rcp_f32_e32 v205, v205
	v_rcp_f32_e32 v206, v206
	v_rcp_f32_e32 v207, v207
	v_lshlrev_b32_e32 v208, 16, v136
	v_and_b32_e32 v209, 0xffff0000, v136
	v_lshlrev_b32_e32 v210, 16, v137
	v_and_b32_e32 v211, 0xffff0000, v137
	v_lshlrev_b32_e32 v212, 16, v138
	v_and_b32_e32 v213, 0xffff0000, v138
	v_lshlrev_b32_e32 v214, 16, v139
	v_and_b32_e32 v215, 0xffff0000, v139
	v_fmac_f32_e32 v80, v200, v208
	v_fmac_f32_e32 v81, v201, v209
	v_fmac_f32_e32 v82, v202, v210
	v_fmac_f32_e32 v83, v203, v211
	v_fmac_f32_e32 v84, v204, v212
	v_fmac_f32_e32 v85, v205, v213
	v_fmac_f32_e32 v86, v206, v214
	v_fmac_f32_e32 v87, v207, v215
	v_mul_f32_e32 v200, 0xbfb8aa3b, v24
	v_mul_f32_e32 v201, 0xbfb8aa3b, v25
	v_mul_f32_e32 v202, 0xbfb8aa3b, v26
	v_mul_f32_e32 v203, 0xbfb8aa3b, v27
	v_mul_f32_e32 v204, 0xbfb8aa3b, v28
	v_mul_f32_e32 v205, 0xbfb8aa3b, v29
	v_mul_f32_e32 v206, 0xbfb8aa3b, v30
	v_mul_f32_e32 v207, 0xbfb8aa3b, v31
	v_exp_f32_e32 v200, v200
	v_exp_f32_e32 v201, v201
	v_exp_f32_e32 v202, v202
	v_exp_f32_e32 v203, v203
	v_exp_f32_e32 v204, v204
	v_exp_f32_e32 v205, v205
	v_exp_f32_e32 v206, v206
	v_exp_f32_e32 v207, v207
	v_add_f32_e32 v200, 1.0, v200
	v_add_f32_e32 v201, 1.0, v201
	v_add_f32_e32 v202, 1.0, v202
	v_add_f32_e32 v203, 1.0, v203
	v_add_f32_e32 v204, 1.0, v204
	v_add_f32_e32 v205, 1.0, v205
	v_add_f32_e32 v206, 1.0, v206
	v_add_f32_e32 v207, 1.0, v207
	v_rcp_f32_e32 v200, v200
	v_rcp_f32_e32 v201, v201
	v_rcp_f32_e32 v202, v202
	v_rcp_f32_e32 v203, v203
	v_rcp_f32_e32 v204, v204
	v_rcp_f32_e32 v205, v205
	v_rcp_f32_e32 v206, v206
	v_rcp_f32_e32 v207, v207
	v_lshlrev_b32_e32 v208, 16, v140
	v_and_b32_e32 v209, 0xffff0000, v140
	v_lshlrev_b32_e32 v210, 16, v141
	v_and_b32_e32 v211, 0xffff0000, v141
	v_lshlrev_b32_e32 v212, 16, v142
	v_and_b32_e32 v213, 0xffff0000, v142
	v_lshlrev_b32_e32 v214, 16, v143
	v_and_b32_e32 v215, 0xffff0000, v143
	v_fmac_f32_e32 v88, v200, v208
	v_fmac_f32_e32 v89, v201, v209
	v_fmac_f32_e32 v90, v202, v210
	v_fmac_f32_e32 v91, v203, v211
	v_fmac_f32_e32 v92, v204, v212
	v_fmac_f32_e32 v93, v205, v213
	v_fmac_f32_e32 v94, v206, v214
	v_fmac_f32_e32 v95, v207, v215
	v_mul_f32_e32 v200, 0xbfb8aa3b, v32
	v_mul_f32_e32 v201, 0xbfb8aa3b, v33
	v_mul_f32_e32 v202, 0xbfb8aa3b, v34
	v_mul_f32_e32 v203, 0xbfb8aa3b, v35
	v_mul_f32_e32 v204, 0xbfb8aa3b, v36
	v_mul_f32_e32 v205, 0xbfb8aa3b, v37
	v_mul_f32_e32 v206, 0xbfb8aa3b, v38
	v_mul_f32_e32 v207, 0xbfb8aa3b, v39
	v_exp_f32_e32 v200, v200
	v_exp_f32_e32 v201, v201
	v_exp_f32_e32 v202, v202
	v_exp_f32_e32 v203, v203
	v_exp_f32_e32 v204, v204
	v_exp_f32_e32 v205, v205
	v_exp_f32_e32 v206, v206
	v_exp_f32_e32 v207, v207
	v_add_f32_e32 v200, 1.0, v200
	v_add_f32_e32 v201, 1.0, v201
	v_add_f32_e32 v202, 1.0, v202
	v_add_f32_e32 v203, 1.0, v203
	v_add_f32_e32 v204, 1.0, v204
	v_add_f32_e32 v205, 1.0, v205
	v_add_f32_e32 v206, 1.0, v206
	v_add_f32_e32 v207, 1.0, v207
	v_rcp_f32_e32 v200, v200
	v_rcp_f32_e32 v201, v201
	v_rcp_f32_e32 v202, v202
	v_rcp_f32_e32 v203, v203
	v_rcp_f32_e32 v204, v204
	v_rcp_f32_e32 v205, v205
	v_rcp_f32_e32 v206, v206
	v_rcp_f32_e32 v207, v207
	v_lshlrev_b32_e32 v208, 16, v148
	v_and_b32_e32 v209, 0xffff0000, v148
	v_lshlrev_b32_e32 v210, 16, v149
	v_and_b32_e32 v211, 0xffff0000, v149
	v_lshlrev_b32_e32 v212, 16, v150
	v_and_b32_e32 v213, 0xffff0000, v150
	v_lshlrev_b32_e32 v214, 16, v151
	v_and_b32_e32 v215, 0xffff0000, v151
	v_fmac_f32_e32 v96, v200, v208
	v_fmac_f32_e32 v97, v201, v209
	v_fmac_f32_e32 v98, v202, v210
	v_fmac_f32_e32 v99, v203, v211
	v_fmac_f32_e32 v100, v204, v212
	v_fmac_f32_e32 v101, v205, v213
	v_fmac_f32_e32 v102, v206, v214
	v_fmac_f32_e32 v103, v207, v215
	v_mul_f32_e32 v200, 0xbfb8aa3b, v40
	v_mul_f32_e32 v201, 0xbfb8aa3b, v41
	v_mul_f32_e32 v202, 0xbfb8aa3b, v42
	v_mul_f32_e32 v203, 0xbfb8aa3b, v43
	v_mul_f32_e32 v204, 0xbfb8aa3b, v44
	v_mul_f32_e32 v205, 0xbfb8aa3b, v45
	v_mul_f32_e32 v206, 0xbfb8aa3b, v46
	v_mul_f32_e32 v207, 0xbfb8aa3b, v47
	v_exp_f32_e32 v200, v200
	v_exp_f32_e32 v201, v201
	v_exp_f32_e32 v202, v202
	v_exp_f32_e32 v203, v203
	v_exp_f32_e32 v204, v204
	v_exp_f32_e32 v205, v205
	v_exp_f32_e32 v206, v206
	v_exp_f32_e32 v207, v207
	v_add_f32_e32 v200, 1.0, v200
	v_add_f32_e32 v201, 1.0, v201
	v_add_f32_e32 v202, 1.0, v202
	v_add_f32_e32 v203, 1.0, v203
	v_add_f32_e32 v204, 1.0, v204
	v_add_f32_e32 v205, 1.0, v205
	v_add_f32_e32 v206, 1.0, v206
	v_add_f32_e32 v207, 1.0, v207
	v_rcp_f32_e32 v200, v200
	v_rcp_f32_e32 v201, v201
	v_rcp_f32_e32 v202, v202
	v_rcp_f32_e32 v203, v203
	v_rcp_f32_e32 v204, v204
	v_rcp_f32_e32 v205, v205
	v_rcp_f32_e32 v206, v206
	v_rcp_f32_e32 v207, v207
	v_lshlrev_b32_e32 v208, 16, v152
	v_and_b32_e32 v209, 0xffff0000, v152
	v_lshlrev_b32_e32 v210, 16, v153
	v_and_b32_e32 v211, 0xffff0000, v153
	v_lshlrev_b32_e32 v212, 16, v154
	v_and_b32_e32 v213, 0xffff0000, v154
	v_lshlrev_b32_e32 v214, 16, v155
; __device__ __forceinline__ float sigmoidf_(float v) { return 1.f / (1.f + __expf(-v)); }
; __device__ void phase_merge4(CParams& p, int l, int tm, int tn, char* smem) {
;     ...
;         unsigned p0 = pk[mi][ni][0], p1 = pk[mi][ni][1], m0 = mer[mi][ni][0], m1 = mer[mi][ni][1];
;         float r0 = __uint_as_float(m0 << 16) + sigmoidf_(acc[mi][ni][0]) * __uint_as_float(p0 << 16);
;         float r1 = __uint_as_float(m0 & 0xffff0000u) + sigmoidf_(acc[mi][ni][1]) * __uint_as_float(p0 & 0xffff0000u);
;         float r2 = __uint_as_float(m1 << 16) + sigmoidf_(acc[mi][ni][2]) * __uint_as_float(p1 << 16);
;         float r3 = __uint_as_float(m1 & 0xffff0000u) + sigmoidf_(acc[mi][ni][3]) * __uint_as_float(p1 & 0xffff0000u);
;         mer[mi][ni][0] = (unsigned)f2bf(r0) | ((unsigned)f2bf(r1) << 16);
;         mer[mi][ni][1] = (unsigned)f2bf(r2) | ((unsigned)f2bf(r3) << 16);
;       }
;   }
;   {
;     const int lane = tid & 63, wid = tid >> 6, wr = wid >> 1, wc = wid & 1;
; #pragma unroll
;     for (int mi = 0; mi < 4; mi++)
; #pragma unroll
;       for (int ni = 0; ni < 4; ni++)
; #pragma unroll
;         for (int j = 0; j < 4; j++) {
;           int rl = wr * 64 + mi * 16 + (lane >> 4) * 4 + j;
;           int cl = wc * 64 + ni * 16 + (lane & 15);
;           unsigned w = mer[mi][ni][j >> 1];
;           p.merged[(size_t)(row0 + rl) * 1024 + col0 + cl] = (bf16_t)((j & 1) ? (w >> 16) : (w & 0xffffu));
	v_and_b32_e32 v215, 0xffff0000, v155
	v_fmac_f32_e32 v104, v200, v208
	v_fmac_f32_e32 v105, v201, v209
	v_fmac_f32_e32 v106, v202, v210
	v_fmac_f32_e32 v107, v203, v211
	v_fmac_f32_e32 v108, v204, v212
	v_fmac_f32_e32 v109, v205, v213
	v_fmac_f32_e32 v110, v206, v214
	v_fmac_f32_e32 v111, v207, v215
	v_mul_f32_e32 v200, 0xbfb8aa3b, v48
	v_mul_f32_e32 v201, 0xbfb8aa3b, v49
	v_mul_f32_e32 v202, 0xbfb8aa3b, v50
	v_mul_f32_e32 v203, 0xbfb8aa3b, v51
	v_mul_f32_e32 v204, 0xbfb8aa3b, v52
	v_mul_f32_e32 v205, 0xbfb8aa3b, v53
	v_mul_f32_e32 v206, 0xbfb8aa3b, v54
	v_mul_f32_e32 v207, 0xbfb8aa3b, v55
	v_exp_f32_e32 v200, v200
	v_exp_f32_e32 v201, v201
	v_exp_f32_e32 v202, v202
	v_exp_f32_e32 v203, v203
	v_exp_f32_e32 v204, v204
	v_exp_f32_e32 v205, v205
	v_exp_f32_e32 v206, v206
	v_exp_f32_e32 v207, v207
	v_add_f32_e32 v200, 1.0, v200
	v_add_f32_e32 v201, 1.0, v201
	v_add_f32_e32 v202, 1.0, v202
	v_add_f32_e32 v203, 1.0, v203
	v_add_f32_e32 v204, 1.0, v204
	v_add_f32_e32 v205, 1.0, v205
	v_add_f32_e32 v206, 1.0, v206
	v_add_f32_e32 v207, 1.0, v207
	v_rcp_f32_e32 v200, v200
	v_rcp_f32_e32 v201, v201
	v_rcp_f32_e32 v202, v202
	v_rcp_f32_e32 v203, v203
	v_rcp_f32_e32 v204, v204
	v_rcp_f32_e32 v205, v205
	v_rcp_f32_e32 v206, v206
	v_rcp_f32_e32 v207, v207
	v_lshlrev_b32_e32 v208, 16, v156
	v_and_b32_e32 v209, 0xffff0000, v156
	v_lshlrev_b32_e32 v210, 16, v157
	v_and_b32_e32 v211, 0xffff0000, v157
	v_lshlrev_b32_e32 v212, 16, v158
	v_and_b32_e32 v213, 0xffff0000, v158
	v_lshlrev_b32_e32 v214, 16, v159
	v_and_b32_e32 v215, 0xffff0000, v159
	v_fmac_f32_e32 v112, v200, v208
	v_fmac_f32_e32 v113, v201, v209
	v_fmac_f32_e32 v114, v202, v210
	v_fmac_f32_e32 v115, v203, v211
	v_fmac_f32_e32 v116, v204, v212
	v_fmac_f32_e32 v117, v205, v213
	v_fmac_f32_e32 v118, v206, v214
	v_fmac_f32_e32 v119, v207, v215
	v_mul_f32_e32 v200, 0xbfb8aa3b, v56
	v_mul_f32_e32 v201, 0xbfb8aa3b, v57
	v_mul_f32_e32 v202, 0xbfb8aa3b, v58
	v_mul_f32_e32 v203, 0xbfb8aa3b, v59
	v_mul_f32_e32 v204, 0xbfb8aa3b, v60
	v_mul_f32_e32 v205, 0xbfb8aa3b, v61
	v_mul_f32_e32 v206, 0xbfb8aa3b, v62
	v_mul_f32_e32 v207, 0xbfb8aa3b, v63
	v_exp_f32_e32 v200, v200
	v_exp_f32_e32 v201, v201
	v_exp_f32_e32 v202, v202
	v_exp_f32_e32 v203, v203
	v_exp_f32_e32 v204, v204
	v_exp_f32_e32 v205, v205
	v_exp_f32_e32 v206, v206
	v_exp_f32_e32 v207, v207
	v_add_f32_e32 v200, 1.0, v200
	v_add_f32_e32 v201, 1.0, v201
	v_add_f32_e32 v202, 1.0, v202
	v_add_f32_e32 v203, 1.0, v203
	v_add_f32_e32 v204, 1.0, v204
	v_add_f32_e32 v205, 1.0, v205
	v_add_f32_e32 v206, 1.0, v206
	v_add_f32_e32 v207, 1.0, v207
	v_rcp_f32_e32 v200, v200
	v_rcp_f32_e32 v201, v201
	v_rcp_f32_e32 v202, v202
	v_rcp_f32_e32 v203, v203
	v_rcp_f32_e32 v204, v204
	v_rcp_f32_e32 v205, v205
	v_rcp_f32_e32 v206, v206
	v_rcp_f32_e32 v207, v207
	v_lshlrev_b32_e32 v208, 16, v160
	v_and_b32_e32 v209, 0xffff0000, v160
	v_lshlrev_b32_e32 v210, 16, v161
	v_and_b32_e32 v211, 0xffff0000, v161
	v_lshlrev_b32_e32 v212, 16, v162
	v_and_b32_e32 v213, 0xffff0000, v162
	v_lshlrev_b32_e32 v214, 16, v163
	v_and_b32_e32 v215, 0xffff0000, v163
	v_fmac_f32_e32 v120, v200, v208
	v_fmac_f32_e32 v121, v201, v209
	v_fmac_f32_e32 v122, v202, v210
	v_fmac_f32_e32 v123, v203, v211
	v_fmac_f32_e32 v124, v204, v212
	v_fmac_f32_e32 v125, v205, v213
	v_fmac_f32_e32 v126, v206, v214
	v_fmac_f32_e32 v127, v207, v215
	s_and_b32 s63, s22, 3
	s_cmp_lg_u32 s63, 3
	s_cbranch_scc1 .Lmg4_nostore
	s_lshl_b32 s62, s23, 11
	s_lshl_b32 s92, s21, 1
	s_add_u32 s62, s62, s92
	s_add_u32 s58, s8, s62
	s_addc_u32 s59, s9, 0
	v_cvt_pk_bf16_f32 v200, v64, v65
	v_cvt_pk_bf16_f32 v201, v66, v67
	v_cvt_pk_bf16_f32 v202, v68, v69
	v_cvt_pk_bf16_f32 v203, v70, v71
	global_store_dwordx4 v144, v[200:203], s[58:59] offset:0
	v_cvt_pk_bf16_f32 v204, v72, v73
	v_cvt_pk_bf16_f32 v205, v74, v75
	v_cvt_pk_bf16_f32 v206, v76, v77
	v_cvt_pk_bf16_f32 v207, v78, v79
	global_store_dwordx4 v144, v[204:207], s[58:59] offset:16
	s_add_u32 s58, s58, 0x8000
	s_addc_u32 s59, s59, 0
	v_cvt_pk_bf16_f32 v208, v80, v81
	v_cvt_pk_bf16_f32 v209, v82, v83
	v_cvt_pk_bf16_f32 v210, v84, v85
	v_cvt_pk_bf16_f32 v211, v86, v87
	global_store_dwordx4 v144, v[208:211], s[58:59] offset:0
	v_cvt_pk_bf16_f32 v212, v88, v89
	v_cvt_pk_bf16_f32 v213, v90, v91
	v_cvt_pk_bf16_f32 v214, v92, v93
	v_cvt_pk_bf16_f32 v215, v94, v95
	global_store_dwordx4 v144, v[212:215], s[58:59] offset:16
	s_add_u32 s58, s58, 0x8000
	s_addc_u32 s59, s59, 0
	v_cvt_pk_bf16_f32 v216, v96, v97
	v_cvt_pk_bf16_f32 v217, v98, v99
	v_cvt_pk_bf16_f32 v218, v100, v101
	v_cvt_pk_bf16_f32 v219, v102, v103
	global_store_dwordx4 v144, v[216:219], s[58:59] offset:0
	v_cvt_pk_bf16_f32 v220, v104, v105
	v_cvt_pk_bf16_f32 v221, v106, v107
	v_cvt_pk_bf16_f32 v222, v108, v109
	v_cvt_pk_bf16_f32 v223, v110, v111
	global_store_dwordx4 v144, v[220:223], s[58:59] offset:16
	s_add_u32 s58, s58, 0x8000
	s_addc_u32 s59, s59, 0
	v_cvt_pk_bf16_f32 v228, v112, v113
	v_cvt_pk_bf16_f32 v229, v114, v115
	v_cvt_pk_bf16_f32 v230, v116, v117
	v_cvt_pk_bf16_f32 v231, v118, v119
	global_store_dwordx4 v144, v[228:231], s[58:59] offset:0
	v_cvt_pk_bf16_f32 v232, v120, v121
	v_cvt_pk_bf16_f32 v233, v122, v123
	v_cvt_pk_bf16_f32 v234, v124, v125
	v_cvt_pk_bf16_f32 v235, v126, v127
	global_store_dwordx4 v144, v[232:235], s[58:59] offset:16
